# v38 + every 32-MFMA segment padded to start 8-byte aligned (one s_nop before s_setprio/s_barrier where needed); half of the segments had their 8-byte MFMA encodings at 4 mod 8
# baseline (speedup 1.0000x reference)
.LBB0_364:
	s_add_u32 s20, s18, 0xfff80080
	s_addc_u32 s21, s19, -1
	s_add_i32 s30, 0, 0x10000
	s_cmp_eq_u32 s29, 28
	s_cselect_b32 s23, s4, s21
	s_cselect_b32 s22, s24, s20
	s_cselect_b32 s21, s25, s28
	s_cselect_b32 s20, s26, s27
	s_add_i32 s42, 0, 0x14000
	v_add_u32_e32 v142, s30, v204
	v_add_u32_e32 v166, s42, v204
	ds_read_b128 v[130:133], v142
	ds_read_b128 v[134:137], v142 offset:1024
	ds_read_b128 v[138:141], v142 offset:2048
	ds_read_b128 v[142:145], v142 offset:3072
	ds_read_b128 v[146:149], v166
	ds_read_b128 v[150:153], v166 offset:1024
	ds_read_b128 v[154:157], v166 offset:2048
	ds_read_b128 v[166:169], v166 offset:3072
	v_lshl_add_u64 v[202:203], s[18:19], 0, v[162:163]
	s_add_i32 m0, s87, 0xc000
	ds_read_b128 v[170:173], v205
	ds_read_b128 v[174:177], v205 offset:1024
	ds_read_b128 v[178:181], v205 offset:2048
	ds_read_b128 v[182:185], v205 offset:3072
	ds_read_b128 v[186:189], v205 offset:4096
	ds_read_b128 v[190:193], v205 offset:5120
	ds_read_b128 v[206:209], v205 offset:6144
	ds_read_b128 v[210:213], v205 offset:7168
	global_load_lds_dwordx4 v[202:203], off
	v_lshl_add_u64 v[202:203], s[18:19], 0, v[164:165]
	s_add_i32 m0, s87, 0xe000
	s_nop 0
	global_load_lds_dwordx4 v[202:203], off
	s_waitcnt vmcnt(8)
	s_waitcnt lgkmcnt(0)
	.p2align 3
	s_setprio 1
	s_barrier
	v_mfma_f32_16x16x32_bf16 v[126:129], v[130:133], v[170:173], v[126:129]
	v_mfma_f32_16x16x32_bf16 v[126:129], v[134:137], v[174:177], v[126:129]
	v_mfma_f32_16x16x32_bf16 v[110:113], v[134:137], v[182:185], v[110:113]
	v_mfma_f32_16x16x32_bf16 v[110:113], v[130:133], v[178:181], v[110:113]
	v_mfma_f32_16x16x32_bf16 v[94:97], v[130:133], v[186:189], v[94:97]
	v_mfma_f32_16x16x32_bf16 v[94:97], v[134:137], v[190:193], v[94:97]
	v_mfma_f32_16x16x32_bf16 v[78:81], v[134:137], v[210:213], v[78:81]
	v_mfma_f32_16x16x32_bf16 v[78:81], v[130:133], v[206:209], v[78:81]
	v_mfma_f32_16x16x32_bf16 v[74:77], v[138:141], v[206:209], v[74:77]
	v_mfma_f32_16x16x32_bf16 v[74:77], v[142:145], v[210:213], v[74:77]
	v_mfma_f32_16x16x32_bf16 v[90:93], v[142:145], v[190:193], v[90:93]
	v_mfma_f32_16x16x32_bf16 v[90:93], v[138:141], v[186:189], v[90:93]
	v_mfma_f32_16x16x32_bf16 v[106:109], v[138:141], v[178:181], v[106:109]
	v_mfma_f32_16x16x32_bf16 v[106:109], v[142:145], v[182:185], v[106:109]
	v_mfma_f32_16x16x32_bf16 v[122:125], v[142:145], v[174:177], v[122:125]
	v_mfma_f32_16x16x32_bf16 v[122:125], v[138:141], v[170:173], v[122:125]
	v_mfma_f32_16x16x32_bf16 v[118:121], v[146:149], v[170:173], v[118:121]
	v_mfma_f32_16x16x32_bf16 v[118:121], v[150:153], v[174:177], v[118:121]
	v_mfma_f32_16x16x32_bf16 v[102:105], v[150:153], v[182:185], v[102:105]
	v_mfma_f32_16x16x32_bf16 v[102:105], v[146:149], v[178:181], v[102:105]
	v_mfma_f32_16x16x32_bf16 v[86:89], v[146:149], v[186:189], v[86:89]
	v_mfma_f32_16x16x32_bf16 v[86:89], v[150:153], v[190:193], v[86:89]
	v_mfma_f32_16x16x32_bf16 v[70:73], v[150:153], v[210:213], v[70:73]
	v_mfma_f32_16x16x32_bf16 v[70:73], v[146:149], v[206:209], v[70:73]
	v_mfma_f32_16x16x32_bf16 v[66:69], v[154:157], v[206:209], v[66:69]
	v_mfma_f32_16x16x32_bf16 v[66:69], v[166:169], v[210:213], v[66:69]
	v_mfma_f32_16x16x32_bf16 v[82:85], v[166:169], v[190:193], v[82:85]
	v_mfma_f32_16x16x32_bf16 v[82:85], v[154:157], v[186:189], v[82:85]
	v_mfma_f32_16x16x32_bf16 v[98:101], v[154:157], v[178:181], v[98:101]
	v_mfma_f32_16x16x32_bf16 v[98:101], v[166:169], v[182:185], v[98:101]
	v_mfma_f32_16x16x32_bf16 v[114:117], v[166:169], v[174:177], v[114:117]
	v_mfma_f32_16x16x32_bf16 v[114:117], v[154:157], v[170:173], v[114:117]
	s_barrier
	s_setprio 0
	s_add_i32 s30, s30, s39
	v_lshl_add_u64 v[202:203], s[20:21], 0, v[158:159]
	s_mov_b32 m0, s30
	ds_read_b128 v[170:173], v205 offset:16384
	ds_read_b128 v[174:177], v205 offset:17408
	ds_read_b128 v[178:181], v205 offset:18432
	ds_read_b128 v[182:185], v205 offset:19456
	ds_read_b128 v[186:189], v205 offset:20480
	ds_read_b128 v[190:193], v205 offset:21504
	ds_read_b128 v[206:209], v205 offset:22528
	ds_read_b128 v[210:213], v205 offset:23552
	global_load_lds_dwordx4 v[202:203], off
	s_add_i32 m0, s30, 0x2000
	s_add_u32 s30, s20, 0x80000
	v_lshl_add_u64 v[214:215], s[20:21], 0, v[160:161]
	s_addc_u32 s31, s21, 0
	s_add_i32 s42, s42, s39
	global_load_lds_dwordx4 v[214:215], off
	v_lshl_add_u64 v[216:217], s[30:31], 0, v[158:159]
	s_mov_b32 m0, s42
	v_lshl_add_u64 v[228:229], s[22:23], 0, v[160:161]
	global_load_lds_dwordx4 v[216:217], off
	v_lshl_add_u64 v[216:217], s[30:31], 0, v[160:161]
	s_add_i32 m0, s42, 0x2000
	s_nop 0
	global_load_lds_dwordx4 v[216:217], off
	v_lshl_add_u64 v[216:217], s[22:23], 0, v[158:159]
	s_mov_b32 m0, s87
	s_nop 0
	global_load_lds_dwordx4 v[216:217], off
	s_mov_b32 m0, s92
	s_nop 0
	global_load_lds_dwordx4 v[228:229], off
	s_waitcnt vmcnt(8)
	s_waitcnt lgkmcnt(0)
	.p2align 3
	s_setprio 1
	s_barrier
	v_mfma_f32_16x16x32_bf16 v[62:65], v[130:133], v[170:173], v[62:65]
	v_mfma_f32_16x16x32_bf16 v[62:65], v[134:137], v[174:177], v[62:65]
	v_mfma_f32_16x16x32_bf16 v[46:49], v[134:137], v[182:185], v[46:49]
	v_mfma_f32_16x16x32_bf16 v[46:49], v[130:133], v[178:181], v[46:49]
	v_mfma_f32_16x16x32_bf16 v[30:33], v[130:133], v[186:189], v[30:33]
	v_mfma_f32_16x16x32_bf16 v[30:33], v[134:137], v[190:193], v[30:33]
	v_mfma_f32_16x16x32_bf16 v[14:17], v[134:137], v[210:213], v[14:17]
	v_mfma_f32_16x16x32_bf16 v[14:17], v[130:133], v[206:209], v[14:17]
	v_mfma_f32_16x16x32_bf16 v[10:13], v[138:141], v[206:209], v[10:13]
	v_mfma_f32_16x16x32_bf16 v[10:13], v[142:145], v[210:213], v[10:13]
	v_mfma_f32_16x16x32_bf16 v[26:29], v[142:145], v[190:193], v[26:29]
	v_mfma_f32_16x16x32_bf16 v[26:29], v[138:141], v[186:189], v[26:29]
	v_mfma_f32_16x16x32_bf16 v[42:45], v[138:141], v[178:181], v[42:45]
	v_mfma_f32_16x16x32_bf16 v[42:45], v[142:145], v[182:185], v[42:45]
	v_mfma_f32_16x16x32_bf16 v[58:61], v[142:145], v[174:177], v[58:61]
	v_mfma_f32_16x16x32_bf16 v[58:61], v[138:141], v[170:173], v[58:61]
	v_mfma_f32_16x16x32_bf16 v[54:57], v[146:149], v[170:173], v[54:57]
	v_mfma_f32_16x16x32_bf16 v[54:57], v[150:153], v[174:177], v[54:57]
	v_mfma_f32_16x16x32_bf16 v[38:41], v[150:153], v[182:185], v[38:41]
	v_mfma_f32_16x16x32_bf16 v[38:41], v[146:149], v[178:181], v[38:41]
	v_mfma_f32_16x16x32_bf16 v[22:25], v[146:149], v[186:189], v[22:25]
	v_mfma_f32_16x16x32_bf16 v[22:25], v[150:153], v[190:193], v[22:25]
	v_mfma_f32_16x16x32_bf16 v[6:9], v[150:153], v[210:213], v[6:9]
	v_mfma_f32_16x16x32_bf16 v[6:9], v[146:149], v[206:209], v[6:9]
	v_mfma_f32_16x16x32_bf16 v[2:5], v[154:157], v[206:209], v[2:5]
	v_mfma_f32_16x16x32_bf16 v[2:5], v[166:169], v[210:213], v[2:5]
	v_mfma_f32_16x16x32_bf16 v[18:21], v[166:169], v[190:193], v[18:21]
	v_mfma_f32_16x16x32_bf16 v[18:21], v[154:157], v[186:189], v[18:21]
	v_mfma_f32_16x16x32_bf16 v[34:37], v[154:157], v[178:181], v[34:37]
	v_mfma_f32_16x16x32_bf16 v[34:37], v[166:169], v[182:185], v[34:37]
	v_mfma_f32_16x16x32_bf16 v[50:53], v[166:169], v[174:177], v[50:53]
	v_mfma_f32_16x16x32_bf16 v[50:53], v[154:157], v[170:173], v[50:53]
	s_barrier
	s_setprio 0
	s_add_i32 s30, 0, 0x18000
	s_add_i32 s31, 0, 0x1c000
	v_add_u32_e32 v142, s30, v204
	v_add_u32_e32 v166, s31, v204
	ds_read_b128 v[130:133], v142
	ds_read_b128 v[134:137], v142 offset:1024
	ds_read_b128 v[138:141], v142 offset:2048
	ds_read_b128 v[142:145], v142 offset:3072
	ds_read_b128 v[146:149], v166
	ds_read_b128 v[150:153], v166 offset:1024
	ds_read_b128 v[154:157], v166 offset:2048
	ds_read_b128 v[166:169], v166 offset:3072
	s_add_u32 s22, s22, 0x80000
	s_addc_u32 s23, s23, 0
	s_mov_b32 m0, s8
	v_lshl_add_u64 v[230:231], s[22:23], 0, v[158:159]
	ds_read_b128 v[170:173], v205 offset:32768
	ds_read_b128 v[174:177], v205 offset:33792
	ds_read_b128 v[178:181], v205 offset:34816
	ds_read_b128 v[182:185], v205 offset:35840
	ds_read_b128 v[186:189], v205 offset:36864
	ds_read_b128 v[190:193], v205 offset:37888
	ds_read_b128 v[206:209], v205 offset:38912
	ds_read_b128 v[210:213], v205 offset:39936
	global_load_lds_dwordx4 v[230:231], off
	v_lshl_add_u64 v[230:231], s[22:23], 0, v[160:161]
	s_mov_b32 m0, s9
	s_nop 0
	global_load_lds_dwordx4 v[230:231], off
	s_waitcnt vmcnt(8)
	s_waitcnt lgkmcnt(0)
	.p2align 3
	s_setprio 1
	s_barrier
	v_mfma_f32_16x16x32_bf16 v[126:129], v[130:133], v[170:173], v[126:129]
	v_mfma_f32_16x16x32_bf16 v[126:129], v[134:137], v[174:177], v[126:129]
	v_mfma_f32_16x16x32_bf16 v[110:113], v[134:137], v[182:185], v[110:113]
	v_mfma_f32_16x16x32_bf16 v[110:113], v[130:133], v[178:181], v[110:113]
	v_mfma_f32_16x16x32_bf16 v[94:97], v[130:133], v[186:189], v[94:97]
	v_mfma_f32_16x16x32_bf16 v[94:97], v[134:137], v[190:193], v[94:97]
	v_mfma_f32_16x16x32_bf16 v[78:81], v[134:137], v[210:213], v[78:81]
	v_mfma_f32_16x16x32_bf16 v[78:81], v[130:133], v[206:209], v[78:81]
	v_mfma_f32_16x16x32_bf16 v[74:77], v[138:141], v[206:209], v[74:77]
	v_mfma_f32_16x16x32_bf16 v[74:77], v[142:145], v[210:213], v[74:77]
	v_mfma_f32_16x16x32_bf16 v[90:93], v[142:145], v[190:193], v[90:93]
	v_mfma_f32_16x16x32_bf16 v[90:93], v[138:141], v[186:189], v[90:93]
	v_mfma_f32_16x16x32_bf16 v[106:109], v[138:141], v[178:181], v[106:109]
	v_mfma_f32_16x16x32_bf16 v[106:109], v[142:145], v[182:185], v[106:109]
	v_mfma_f32_16x16x32_bf16 v[122:125], v[142:145], v[174:177], v[122:125]
	v_mfma_f32_16x16x32_bf16 v[122:125], v[138:141], v[170:173], v[122:125]
	v_mfma_f32_16x16x32_bf16 v[118:121], v[146:149], v[170:173], v[118:121]
	v_mfma_f32_16x16x32_bf16 v[118:121], v[150:153], v[174:177], v[118:121]
	v_mfma_f32_16x16x32_bf16 v[102:105], v[150:153], v[182:185], v[102:105]
	v_mfma_f32_16x16x32_bf16 v[102:105], v[146:149], v[178:181], v[102:105]
	v_mfma_f32_16x16x32_bf16 v[86:89], v[146:149], v[186:189], v[86:89]
	v_mfma_f32_16x16x32_bf16 v[86:89], v[150:153], v[190:193], v[86:89]
	v_mfma_f32_16x16x32_bf16 v[70:73], v[150:153], v[210:213], v[70:73]
	v_mfma_f32_16x16x32_bf16 v[70:73], v[146:149], v[206:209], v[70:73]
	v_mfma_f32_16x16x32_bf16 v[66:69], v[154:157], v[206:209], v[66:69]
	v_mfma_f32_16x16x32_bf16 v[66:69], v[166:169], v[210:213], v[66:69]
	v_mfma_f32_16x16x32_bf16 v[82:85], v[166:169], v[190:193], v[82:85]
	v_mfma_f32_16x16x32_bf16 v[82:85], v[154:157], v[186:189], v[82:85]
	v_mfma_f32_16x16x32_bf16 v[98:101], v[154:157], v[178:181], v[98:101]
	v_mfma_f32_16x16x32_bf16 v[98:101], v[166:169], v[182:185], v[98:101]
	v_mfma_f32_16x16x32_bf16 v[114:117], v[166:169], v[174:177], v[114:117]
	v_mfma_f32_16x16x32_bf16 v[114:117], v[154:157], v[170:173], v[114:117]
	s_barrier
	s_setprio 0
	s_add_i32 s22, s30, s39
	v_lshl_add_u64 v[202:203], v[202:203], 0, s[10:11]
	s_mov_b32 m0, s22
	ds_read_b128 v[170:173], v205 offset:49152
	ds_read_b128 v[174:177], v205 offset:50176
	ds_read_b128 v[178:181], v205 offset:51200
	ds_read_b128 v[182:185], v205 offset:52224
	ds_read_b128 v[186:189], v205 offset:53248
	ds_read_b128 v[190:193], v205 offset:54272
	ds_read_b128 v[206:209], v205 offset:55296
	ds_read_b128 v[210:213], v205 offset:56320
	global_load_lds_dwordx4 v[202:203], off
	s_add_i32 m0, s22, 0x2000
	s_add_u32 s20, s20, 0x80080
	v_lshl_add_u64 v[202:203], v[214:215], 0, s[10:11]
	s_addc_u32 s21, s21, 0
	s_add_i32 s22, s31, s39
	global_load_lds_dwordx4 v[202:203], off
	v_lshl_add_u64 v[202:203], s[20:21], 0, v[158:159]
	s_mov_b32 m0, s22
	s_nop 0
	global_load_lds_dwordx4 v[202:203], off
	v_lshl_add_u64 v[202:203], s[20:21], 0, v[160:161]
	s_add_i32 m0, s22, 0x2000
	s_nop 0
	global_load_lds_dwordx4 v[202:203], off
	v_lshl_add_u64 v[202:203], v[216:217], 0, s[10:11]
	s_mov_b32 m0, s56
	s_nop 0
	global_load_lds_dwordx4 v[202:203], off
	v_lshl_add_u64 v[202:203], v[228:229], 0, s[10:11]
	s_mov_b32 m0, s57
	s_nop 0
	global_load_lds_dwordx4 v[202:203], off
	s_waitcnt vmcnt(8)
	s_waitcnt lgkmcnt(0)
	.p2align 3
	s_setprio 1
	s_barrier
	v_mfma_f32_16x16x32_bf16 v[62:65], v[130:133], v[170:173], v[62:65]
	v_mfma_f32_16x16x32_bf16 v[62:65], v[134:137], v[174:177], v[62:65]
	v_mfma_f32_16x16x32_bf16 v[46:49], v[134:137], v[182:185], v[46:49]
	v_mfma_f32_16x16x32_bf16 v[46:49], v[130:133], v[178:181], v[46:49]
	v_mfma_f32_16x16x32_bf16 v[30:33], v[130:133], v[186:189], v[30:33]
	v_mfma_f32_16x16x32_bf16 v[30:33], v[134:137], v[190:193], v[30:33]
	v_mfma_f32_16x16x32_bf16 v[14:17], v[134:137], v[210:213], v[14:17]
	v_mfma_f32_16x16x32_bf16 v[14:17], v[130:133], v[206:209], v[14:17]
	v_mfma_f32_16x16x32_bf16 v[10:13], v[138:141], v[206:209], v[10:13]
	v_mfma_f32_16x16x32_bf16 v[10:13], v[142:145], v[210:213], v[10:13]
	v_mfma_f32_16x16x32_bf16 v[26:29], v[142:145], v[190:193], v[26:29]
	v_mfma_f32_16x16x32_bf16 v[26:29], v[138:141], v[186:189], v[26:29]
	v_mfma_f32_16x16x32_bf16 v[42:45], v[138:141], v[178:181], v[42:45]
	v_mfma_f32_16x16x32_bf16 v[42:45], v[142:145], v[182:185], v[42:45]
	v_mfma_f32_16x16x32_bf16 v[58:61], v[142:145], v[174:177], v[58:61]
	v_mfma_f32_16x16x32_bf16 v[58:61], v[138:141], v[170:173], v[58:61]
	v_mfma_f32_16x16x32_bf16 v[54:57], v[146:149], v[170:173], v[54:57]
	v_mfma_f32_16x16x32_bf16 v[54:57], v[150:153], v[174:177], v[54:57]
	v_mfma_f32_16x16x32_bf16 v[38:41], v[150:153], v[182:185], v[38:41]
	v_mfma_f32_16x16x32_bf16 v[38:41], v[146:149], v[178:181], v[38:41]
	v_mfma_f32_16x16x32_bf16 v[22:25], v[146:149], v[186:189], v[22:25]
	v_mfma_f32_16x16x32_bf16 v[22:25], v[150:153], v[190:193], v[22:25]
	v_mfma_f32_16x16x32_bf16 v[6:9], v[150:153], v[210:213], v[6:9]
	v_mfma_f32_16x16x32_bf16 v[6:9], v[146:149], v[206:209], v[6:9]
	v_mfma_f32_16x16x32_bf16 v[2:5], v[154:157], v[206:209], v[2:5]
	v_mfma_f32_16x16x32_bf16 v[2:5], v[166:169], v[210:213], v[2:5]
	v_mfma_f32_16x16x32_bf16 v[18:21], v[166:169], v[190:193], v[18:21]
	v_mfma_f32_16x16x32_bf16 v[18:21], v[154:157], v[186:189], v[18:21]
	v_mfma_f32_16x16x32_bf16 v[34:37], v[154:157], v[178:181], v[34:37]
	v_mfma_f32_16x16x32_bf16 v[34:37], v[166:169], v[182:185], v[34:37]
	v_mfma_f32_16x16x32_bf16 v[50:53], v[166:169], v[174:177], v[50:53]
	v_mfma_f32_16x16x32_bf16 v[50:53], v[154:157], v[170:173], v[50:53]
	s_barrier
	s_setprio 0
	s_add_i32 s29, s29, 2
	s_add_u32 s18, s18, 0x100
	s_addc_u32 s19, s19, 0
	s_add_u32 s27, s27, 0x100
	s_addc_u32 s28, s28, 0
	s_cmp_gt_u32 s29, 29
	s_cbranch_scc0 .LBB0_364
	s_and_b64 vcc, exec, s[58:59]
	s_cbranch_vccz .LBB0_367
	s_barrier

.LBB0_986:
	s_add_u32 s24, s22, 0x100
	s_addc_u32 s25, s23, 0
	s_add_i32 s62, 0, 0x10000
	s_cmp_eq_u32 s61, 28
	s_cselect_b32 s29, s17, s25
	s_cselect_b32 s28, s58, s24
	v_add_u32_e32 v138, s62, v140
	s_cselect_b32 s27, s19, s60
	s_cselect_b32 s26, s18, s59
	s_add_i32 s63, 0, 0x14000
	ds_read_b128 v[142:145], v138
	ds_read_b128 v[146:149], v138 offset:1024
	ds_read_b128 v[150:153], v138 offset:2048
	ds_read_b128 v[154:157], v138 offset:3072
	v_add_u32_e32 v138, s63, v140
	ds_read_b128 v[158:161], v138
	ds_read_b128 v[162:165], v138 offset:1024
	ds_read_b128 v[166:169], v138 offset:2048
	ds_read_b128 v[170:173], v138 offset:3072
	v_lshl_add_u64 v[138:139], s[22:23], 0, v[134:135]
	s_add_i32 m0, s47, 0xc000
	ds_read_b128 v[174:177], v141
	ds_read_b128 v[178:181], v141 offset:1024
	ds_read_b128 v[182:185], v141 offset:2048
	ds_read_b128 v[186:189], v141 offset:3072
	ds_read_b128 v[190:193], v141 offset:4096
	ds_read_b128 v[202:205], v141 offset:5120
	ds_read_b128 v[206:209], v141 offset:6144
	ds_read_b128 v[210:213], v141 offset:7168
	global_load_lds_dwordx4 v[138:139], off
	v_lshl_add_u64 v[138:139], s[22:23], 0, v[136:137]
	s_add_i32 m0, s47, 0xe000
	s_nop 0
	global_load_lds_dwordx4 v[138:139], off
	s_waitcnt vmcnt(8)
	s_waitcnt lgkmcnt(0)
	.p2align 3
	s_setprio 1
	s_barrier
	v_mfma_f32_16x16x32_bf16 v[126:129], v[142:145], v[174:177], v[126:129]
	v_mfma_f32_16x16x32_bf16 v[126:129], v[146:149], v[178:181], v[126:129]
	v_mfma_f32_16x16x32_bf16 v[118:121], v[146:149], v[186:189], v[118:121]
	v_mfma_f32_16x16x32_bf16 v[118:121], v[142:145], v[182:185], v[118:121]
	v_mfma_f32_16x16x32_bf16 v[102:105], v[142:145], v[190:193], v[102:105]
	v_mfma_f32_16x16x32_bf16 v[102:105], v[146:149], v[202:205], v[102:105]
	v_mfma_f32_16x16x32_bf16 v[86:89], v[146:149], v[210:213], v[86:89]
	v_mfma_f32_16x16x32_bf16 v[86:89], v[142:145], v[206:209], v[86:89]
	v_mfma_f32_16x16x32_bf16 v[78:81], v[150:153], v[206:209], v[78:81]
	v_mfma_f32_16x16x32_bf16 v[78:81], v[154:157], v[210:213], v[78:81]
	v_mfma_f32_16x16x32_bf16 v[94:97], v[154:157], v[202:205], v[94:97]
	v_mfma_f32_16x16x32_bf16 v[94:97], v[150:153], v[190:193], v[94:97]
	v_mfma_f32_16x16x32_bf16 v[110:113], v[150:153], v[182:185], v[110:113]
	v_mfma_f32_16x16x32_bf16 v[110:113], v[154:157], v[186:189], v[110:113]
	v_mfma_f32_16x16x32_bf16 v[122:125], v[154:157], v[178:181], v[122:125]
	v_mfma_f32_16x16x32_bf16 v[122:125], v[150:153], v[174:177], v[122:125]
	v_mfma_f32_16x16x32_bf16 v[114:117], v[158:161], v[174:177], v[114:117]
	v_mfma_f32_16x16x32_bf16 v[114:117], v[162:165], v[178:181], v[114:117]
	v_mfma_f32_16x16x32_bf16 v[98:101], v[162:165], v[186:189], v[98:101]
	v_mfma_f32_16x16x32_bf16 v[98:101], v[158:161], v[182:185], v[98:101]
	v_mfma_f32_16x16x32_bf16 v[82:85], v[158:161], v[190:193], v[82:85]
	v_mfma_f32_16x16x32_bf16 v[82:85], v[162:165], v[202:205], v[82:85]
	v_mfma_f32_16x16x32_bf16 v[70:73], v[162:165], v[210:213], v[70:73]
	v_mfma_f32_16x16x32_bf16 v[70:73], v[158:161], v[206:209], v[70:73]
	v_mfma_f32_16x16x32_bf16 v[66:69], v[166:169], v[206:209], v[66:69]
	v_mfma_f32_16x16x32_bf16 v[66:69], v[170:173], v[210:213], v[66:69]
	v_mfma_f32_16x16x32_bf16 v[74:77], v[170:173], v[202:205], v[74:77]
	v_mfma_f32_16x16x32_bf16 v[74:77], v[166:169], v[190:193], v[74:77]
	v_mfma_f32_16x16x32_bf16 v[90:93], v[166:169], v[182:185], v[90:93]
	v_mfma_f32_16x16x32_bf16 v[90:93], v[170:173], v[186:189], v[90:93]
	v_mfma_f32_16x16x32_bf16 v[106:109], v[170:173], v[178:181], v[106:109]
	v_mfma_f32_16x16x32_bf16 v[106:109], v[166:169], v[174:177], v[106:109]
	s_barrier
	s_setprio 0
	s_add_i32 s22, s62, s36
	v_lshl_add_u64 v[138:139], s[26:27], 0, v[132:133]
	s_mov_b32 m0, s22
	ds_read_b128 v[174:177], v141 offset:16384
	ds_read_b128 v[178:181], v141 offset:17408
	ds_read_b128 v[182:185], v141 offset:18432
	ds_read_b128 v[186:189], v141 offset:19456
	ds_read_b128 v[190:193], v141 offset:20480
	ds_read_b128 v[202:205], v141 offset:21504
	ds_read_b128 v[206:209], v141 offset:22528
	ds_read_b128 v[210:213], v141 offset:23552
	global_load_lds_dwordx4 v[138:139], off
	s_add_i32 m0, s22, 0x2000
	s_add_u32 s22, s26, 0x80000
	v_lshl_add_u64 v[214:215], s[26:27], 0, v[130:131]
	s_addc_u32 s23, s27, 0
	s_add_i32 s62, s63, s36
	global_load_lds_dwordx4 v[214:215], off
	v_lshl_add_u64 v[216:217], s[22:23], 0, v[132:133]
	s_mov_b32 m0, s62
	v_lshl_add_u64 v[228:229], s[28:29], 0, v[130:131]
	global_load_lds_dwordx4 v[216:217], off
	v_lshl_add_u64 v[216:217], s[22:23], 0, v[130:131]
	s_add_i32 m0, s62, 0x2000
	s_nop 0
	global_load_lds_dwordx4 v[216:217], off
	v_lshl_add_u64 v[216:217], s[28:29], 0, v[132:133]
	s_mov_b32 m0, s47
	s_nop 0
	global_load_lds_dwordx4 v[216:217], off
	s_mov_b32 m0, s48
	s_nop 0
	global_load_lds_dwordx4 v[228:229], off
	s_waitcnt vmcnt(8)
	s_waitcnt lgkmcnt(0)
	.p2align 3
	s_setprio 1
	s_barrier
	v_mfma_f32_16x16x32_bf16 v[62:65], v[142:145], v[174:177], v[62:65]
	v_mfma_f32_16x16x32_bf16 v[62:65], v[146:149], v[178:181], v[62:65]
	v_mfma_f32_16x16x32_bf16 v[54:57], v[146:149], v[186:189], v[54:57]
	v_mfma_f32_16x16x32_bf16 v[54:57], v[142:145], v[182:185], v[54:57]
	v_mfma_f32_16x16x32_bf16 v[38:41], v[142:145], v[190:193], v[38:41]
	v_mfma_f32_16x16x32_bf16 v[38:41], v[146:149], v[202:205], v[38:41]
	v_mfma_f32_16x16x32_bf16 v[22:25], v[146:149], v[210:213], v[22:25]
	v_mfma_f32_16x16x32_bf16 v[22:25], v[142:145], v[206:209], v[22:25]
	v_mfma_f32_16x16x32_bf16 v[14:17], v[150:153], v[206:209], v[14:17]
	v_mfma_f32_16x16x32_bf16 v[14:17], v[154:157], v[210:213], v[14:17]
	v_mfma_f32_16x16x32_bf16 v[30:33], v[154:157], v[202:205], v[30:33]
	v_mfma_f32_16x16x32_bf16 v[30:33], v[150:153], v[190:193], v[30:33]
	v_mfma_f32_16x16x32_bf16 v[46:49], v[150:153], v[182:185], v[46:49]
	v_mfma_f32_16x16x32_bf16 v[46:49], v[154:157], v[186:189], v[46:49]
	v_mfma_f32_16x16x32_bf16 v[58:61], v[154:157], v[178:181], v[58:61]
	v_mfma_f32_16x16x32_bf16 v[58:61], v[150:153], v[174:177], v[58:61]
	v_mfma_f32_16x16x32_bf16 v[50:53], v[158:161], v[174:177], v[50:53]
	v_mfma_f32_16x16x32_bf16 v[50:53], v[162:165], v[178:181], v[50:53]
	v_mfma_f32_16x16x32_bf16 v[34:37], v[162:165], v[186:189], v[34:37]
	v_mfma_f32_16x16x32_bf16 v[34:37], v[158:161], v[182:185], v[34:37]
	v_mfma_f32_16x16x32_bf16 v[18:21], v[158:161], v[190:193], v[18:21]
	v_mfma_f32_16x16x32_bf16 v[18:21], v[162:165], v[202:205], v[18:21]
	v_mfma_f32_16x16x32_bf16 v[6:9], v[162:165], v[210:213], v[6:9]
	v_mfma_f32_16x16x32_bf16 v[6:9], v[158:161], v[206:209], v[6:9]
	v_mfma_f32_16x16x32_bf16 v[2:5], v[166:169], v[206:209], v[2:5]
	v_mfma_f32_16x16x32_bf16 v[2:5], v[170:173], v[210:213], v[2:5]
	v_mfma_f32_16x16x32_bf16 v[10:13], v[170:173], v[202:205], v[10:13]
	v_mfma_f32_16x16x32_bf16 v[10:13], v[166:169], v[190:193], v[10:13]
	v_mfma_f32_16x16x32_bf16 v[26:29], v[166:169], v[182:185], v[26:29]
	v_mfma_f32_16x16x32_bf16 v[26:29], v[170:173], v[186:189], v[26:29]
	v_mfma_f32_16x16x32_bf16 v[42:45], v[170:173], v[178:181], v[42:45]
	v_mfma_f32_16x16x32_bf16 v[42:45], v[166:169], v[174:177], v[42:45]
	s_barrier
	s_setprio 0
	s_add_i32 s62, 0, 0x18000
	s_add_i32 s63, 0, 0x1c000
	v_add_u32_e32 v154, s62, v140
	v_add_u32_e32 v170, s63, v140
	ds_read_b128 v[142:145], v154
	ds_read_b128 v[146:149], v154 offset:1024
	ds_read_b128 v[150:153], v154 offset:2048
	ds_read_b128 v[154:157], v154 offset:3072
	ds_read_b128 v[158:161], v170
	ds_read_b128 v[162:165], v170 offset:1024
	ds_read_b128 v[166:169], v170 offset:2048
	ds_read_b128 v[170:173], v170 offset:3072
	s_add_u32 s22, s28, 0x80000
	s_addc_u32 s23, s29, 0
	s_mov_b32 m0, s49
	v_lshl_add_u64 v[230:231], s[22:23], 0, v[132:133]
	ds_read_b128 v[174:177], v141 offset:32768
	ds_read_b128 v[178:181], v141 offset:33792
	ds_read_b128 v[182:185], v141 offset:34816
	ds_read_b128 v[186:189], v141 offset:35840
	ds_read_b128 v[190:193], v141 offset:36864
	ds_read_b128 v[202:205], v141 offset:37888
	ds_read_b128 v[206:209], v141 offset:38912
	ds_read_b128 v[210:213], v141 offset:39936
	global_load_lds_dwordx4 v[230:231], off
	v_lshl_add_u64 v[230:231], s[22:23], 0, v[130:131]
	s_mov_b32 m0, s50
	s_nop 0
	global_load_lds_dwordx4 v[230:231], off
	s_waitcnt vmcnt(8)
	s_waitcnt lgkmcnt(0)
	.p2align 3
	s_setprio 1
	s_barrier
	v_mfma_f32_16x16x32_bf16 v[126:129], v[142:145], v[174:177], v[126:129]
	v_mfma_f32_16x16x32_bf16 v[126:129], v[146:149], v[178:181], v[126:129]
	v_mfma_f32_16x16x32_bf16 v[118:121], v[146:149], v[186:189], v[118:121]
	v_mfma_f32_16x16x32_bf16 v[118:121], v[142:145], v[182:185], v[118:121]
	v_mfma_f32_16x16x32_bf16 v[102:105], v[142:145], v[190:193], v[102:105]
	v_mfma_f32_16x16x32_bf16 v[102:105], v[146:149], v[202:205], v[102:105]
	v_mfma_f32_16x16x32_bf16 v[86:89], v[146:149], v[210:213], v[86:89]
	v_mfma_f32_16x16x32_bf16 v[86:89], v[142:145], v[206:209], v[86:89]
	v_mfma_f32_16x16x32_bf16 v[78:81], v[150:153], v[206:209], v[78:81]
	v_mfma_f32_16x16x32_bf16 v[78:81], v[154:157], v[210:213], v[78:81]
	v_mfma_f32_16x16x32_bf16 v[94:97], v[154:157], v[202:205], v[94:97]
	v_mfma_f32_16x16x32_bf16 v[94:97], v[150:153], v[190:193], v[94:97]
	v_mfma_f32_16x16x32_bf16 v[110:113], v[150:153], v[182:185], v[110:113]
	v_mfma_f32_16x16x32_bf16 v[110:113], v[154:157], v[186:189], v[110:113]
	v_mfma_f32_16x16x32_bf16 v[122:125], v[154:157], v[178:181], v[122:125]
	v_mfma_f32_16x16x32_bf16 v[122:125], v[150:153], v[174:177], v[122:125]
	v_mfma_f32_16x16x32_bf16 v[114:117], v[158:161], v[174:177], v[114:117]
	v_mfma_f32_16x16x32_bf16 v[114:117], v[162:165], v[178:181], v[114:117]
	v_mfma_f32_16x16x32_bf16 v[98:101], v[162:165], v[186:189], v[98:101]
	v_mfma_f32_16x16x32_bf16 v[98:101], v[158:161], v[182:185], v[98:101]
	v_mfma_f32_16x16x32_bf16 v[82:85], v[158:161], v[190:193], v[82:85]
	v_mfma_f32_16x16x32_bf16 v[82:85], v[162:165], v[202:205], v[82:85]
	v_mfma_f32_16x16x32_bf16 v[70:73], v[162:165], v[210:213], v[70:73]
	v_mfma_f32_16x16x32_bf16 v[70:73], v[158:161], v[206:209], v[70:73]
	v_mfma_f32_16x16x32_bf16 v[66:69], v[166:169], v[206:209], v[66:69]
	v_mfma_f32_16x16x32_bf16 v[66:69], v[170:173], v[210:213], v[66:69]
	v_mfma_f32_16x16x32_bf16 v[74:77], v[170:173], v[202:205], v[74:77]
	v_mfma_f32_16x16x32_bf16 v[74:77], v[166:169], v[190:193], v[74:77]
	v_mfma_f32_16x16x32_bf16 v[90:93], v[166:169], v[182:185], v[90:93]
	v_mfma_f32_16x16x32_bf16 v[90:93], v[170:173], v[186:189], v[90:93]
	v_mfma_f32_16x16x32_bf16 v[106:109], v[170:173], v[178:181], v[106:109]
	v_mfma_f32_16x16x32_bf16 v[106:109], v[166:169], v[174:177], v[106:109]
	s_barrier
	s_setprio 0
	s_add_i32 s22, s62, s36
	v_lshl_add_u64 v[138:139], v[138:139], 0, s[10:11]
	s_mov_b32 m0, s22
	ds_read_b128 v[174:177], v141 offset:49152
	ds_read_b128 v[178:181], v141 offset:50176
	ds_read_b128 v[182:185], v141 offset:51200
	ds_read_b128 v[186:189], v141 offset:52224
	ds_read_b128 v[190:193], v141 offset:53248
	ds_read_b128 v[202:205], v141 offset:54272
	ds_read_b128 v[206:209], v141 offset:55296
	ds_read_b128 v[210:213], v141 offset:56320
	global_load_lds_dwordx4 v[138:139], off
	s_add_i32 m0, s22, 0x2000
	s_add_u32 s22, s26, 0x80080
	v_lshl_add_u64 v[138:139], v[214:215], 0, s[10:11]
	s_addc_u32 s23, s27, 0
	s_add_i32 s26, s63, s36
	global_load_lds_dwordx4 v[138:139], off
	v_lshl_add_u64 v[138:139], s[22:23], 0, v[132:133]
	s_mov_b32 m0, s26
	s_nop 0
	global_load_lds_dwordx4 v[138:139], off
	v_lshl_add_u64 v[138:139], s[22:23], 0, v[130:131]
	s_add_i32 m0, s26, 0x2000
	s_nop 0
	global_load_lds_dwordx4 v[138:139], off
	v_lshl_add_u64 v[138:139], v[216:217], 0, s[10:11]
	s_mov_b32 m0, s51
	s_nop 0
	global_load_lds_dwordx4 v[138:139], off
	v_lshl_add_u64 v[138:139], v[228:229], 0, s[10:11]
	s_mov_b32 m0, s52
	s_nop 0
	global_load_lds_dwordx4 v[138:139], off
	s_waitcnt vmcnt(8)
	s_waitcnt lgkmcnt(0)
	.p2align 3
	s_setprio 1
	s_barrier
	v_mfma_f32_16x16x32_bf16 v[62:65], v[142:145], v[174:177], v[62:65]
	v_mfma_f32_16x16x32_bf16 v[62:65], v[146:149], v[178:181], v[62:65]
	v_mfma_f32_16x16x32_bf16 v[54:57], v[146:149], v[186:189], v[54:57]
	v_mfma_f32_16x16x32_bf16 v[54:57], v[142:145], v[182:185], v[54:57]
	v_mfma_f32_16x16x32_bf16 v[38:41], v[142:145], v[190:193], v[38:41]
	v_mfma_f32_16x16x32_bf16 v[38:41], v[146:149], v[202:205], v[38:41]
	v_mfma_f32_16x16x32_bf16 v[22:25], v[146:149], v[210:213], v[22:25]
	v_mfma_f32_16x16x32_bf16 v[22:25], v[142:145], v[206:209], v[22:25]
	v_mfma_f32_16x16x32_bf16 v[14:17], v[150:153], v[206:209], v[14:17]
	v_mfma_f32_16x16x32_bf16 v[14:17], v[154:157], v[210:213], v[14:17]
	v_mfma_f32_16x16x32_bf16 v[30:33], v[154:157], v[202:205], v[30:33]
	v_mfma_f32_16x16x32_bf16 v[30:33], v[150:153], v[190:193], v[30:33]
	v_mfma_f32_16x16x32_bf16 v[46:49], v[150:153], v[182:185], v[46:49]
	v_mfma_f32_16x16x32_bf16 v[46:49], v[154:157], v[186:189], v[46:49]
	v_mfma_f32_16x16x32_bf16 v[58:61], v[154:157], v[178:181], v[58:61]
	v_mfma_f32_16x16x32_bf16 v[58:61], v[150:153], v[174:177], v[58:61]
	v_mfma_f32_16x16x32_bf16 v[50:53], v[158:161], v[174:177], v[50:53]
	v_mfma_f32_16x16x32_bf16 v[50:53], v[162:165], v[178:181], v[50:53]
	v_mfma_f32_16x16x32_bf16 v[34:37], v[162:165], v[186:189], v[34:37]
	v_mfma_f32_16x16x32_bf16 v[34:37], v[158:161], v[182:185], v[34:37]
	v_mfma_f32_16x16x32_bf16 v[18:21], v[158:161], v[190:193], v[18:21]
	v_mfma_f32_16x16x32_bf16 v[18:21], v[162:165], v[202:205], v[18:21]
	v_mfma_f32_16x16x32_bf16 v[6:9], v[162:165], v[210:213], v[6:9]
	v_mfma_f32_16x16x32_bf16 v[6:9], v[158:161], v[206:209], v[6:9]
	v_mfma_f32_16x16x32_bf16 v[2:5], v[166:169], v[206:209], v[2:5]
	v_mfma_f32_16x16x32_bf16 v[2:5], v[170:173], v[210:213], v[2:5]
	v_mfma_f32_16x16x32_bf16 v[10:13], v[170:173], v[202:205], v[10:13]
	v_mfma_f32_16x16x32_bf16 v[10:13], v[166:169], v[190:193], v[10:13]
	v_mfma_f32_16x16x32_bf16 v[26:29], v[166:169], v[182:185], v[26:29]
	v_mfma_f32_16x16x32_bf16 v[26:29], v[170:173], v[186:189], v[26:29]
	v_mfma_f32_16x16x32_bf16 v[42:45], v[170:173], v[178:181], v[42:45]
	v_mfma_f32_16x16x32_bf16 v[42:45], v[166:169], v[174:177], v[42:45]
	s_barrier
	s_setprio 0
	s_add_i32 s61, s61, 2
	s_add_u32 s59, s59, 0x100
	s_addc_u32 s60, s60, 0
	s_cmp_gt_u32 s61, 29
	s_mov_b64 s[22:23], s[24:25]
	s_cbranch_scc0 .LBB0_986
	s_and_b64 vcc, exec, s[14:15]
	s_cbranch_vccz .LBB0_989
	s_barrier

.LBB0_1002:
	s_add_i32 s36, s21, 0x100
	s_and_b64 s[30:31], s[28:29], exec
	s_cselect_b32 s31, 0, s36
	s_cselect_b32 s30, 0, 0
	s_add_u32 s36, s8, s31
	s_addc_u32 s37, s9, s30
	s_add_u32 s30, s24, s21
	s_addc_u32 s31, s25, 0
	s_add_u32 s30, s30, 0x100
	s_addc_u32 s31, s31, 0
	s_add_i32 s71, 0, 0x10000
	s_and_b64 s[28:29], s[28:29], exec
	s_cselect_b32 s39, s19, s31
	s_cselect_b32 s38, s18, s30
	s_add_i32 s29, 0, 0x14000
	s_add_u32 s21, s44, s21
	s_addc_u32 s28, s45, 0
	s_add_u32 s48, s21, 0x17110080
	s_addc_u32 s49, s28, 0
	s_add_i32 s70, s71, s52
	s_add_i32 m0, s53, 0xc000
	s_add_i32 s73, s53, 0xe000
	s_add_i32 s67, s70, 0x2000
	v_add_u32_e32 v134, s71, v136
	s_add_u32 s46, s38, 0x10000
	ds_read_b128 v[138:141], v134
	ds_read_b128 v[142:145], v134 offset:1024
	ds_read_b128 v[146:149], v134 offset:2048
	ds_read_b128 v[150:153], v134 offset:3072
	v_add_u32_e32 v134, s29, v136
	s_addc_u32 s47, s39, 0
	s_add_i32 s69, s29, s52
	ds_read_b128 v[154:157], v134
	ds_read_b128 v[158:161], v134 offset:1024
	ds_read_b128 v[162:165], v134 offset:2048
	ds_read_b128 v[166:169], v134 offset:3072
	s_add_i32 s68, s69, 0x2000
	s_add_i32 s66, 0, 0x18000
	s_add_i32 s65, 0, 0x1c000
	s_add_u32 s30, s36, 0x10000
	s_addc_u32 s31, s37, 0
	s_add_i32 s64, s66, s52
	s_add_i32 s21, s64, 0x2000
	s_add_u32 s28, s38, 0x10080
	s_addc_u32 s29, s39, 0
	s_add_i32 s72, s65, s52
	s_add_i32 s71, s72, 0x2000
	v_lshl_add_u64 v[134:135], s[48:49], 0, v[132:133]
	ds_read_b128 v[170:173], v137
	ds_read_b128 v[174:177], v137 offset:1024
	ds_read_b128 v[178:181], v137 offset:2048
	ds_read_b128 v[182:185], v137 offset:3072
	ds_read_b128 v[186:189], v137 offset:4096
	ds_read_b128 v[190:193], v137 offset:5120
	ds_read_b128 v[202:205], v137 offset:6144
	ds_read_b128 v[206:209], v137 offset:7168
	global_load_lds_dwordx4 v[134:135], off
	v_lshl_add_u64 v[134:135], s[48:49], 0, v[130:131]
	s_mov_b32 m0, s73
	s_nop 0
	global_load_lds_dwordx4 v[134:135], off
	s_waitcnt vmcnt(8)
	s_waitcnt lgkmcnt(0)
	.p2align 3
	s_setprio 1
	s_barrier
	v_mfma_f32_16x16x32_bf16 v[126:129], v[138:141], v[170:173], v[126:129]
	v_mfma_f32_16x16x32_bf16 v[126:129], v[142:145], v[174:177], v[126:129]
	v_mfma_f32_16x16x32_bf16 v[118:121], v[142:145], v[182:185], v[118:121]
	v_mfma_f32_16x16x32_bf16 v[118:121], v[138:141], v[178:181], v[118:121]
	v_mfma_f32_16x16x32_bf16 v[102:105], v[138:141], v[186:189], v[102:105]
	v_mfma_f32_16x16x32_bf16 v[102:105], v[142:145], v[190:193], v[102:105]
	v_mfma_f32_16x16x32_bf16 v[86:89], v[142:145], v[206:209], v[86:89]
	v_mfma_f32_16x16x32_bf16 v[86:89], v[138:141], v[202:205], v[86:89]
	v_mfma_f32_16x16x32_bf16 v[78:81], v[146:149], v[202:205], v[78:81]
	v_mfma_f32_16x16x32_bf16 v[78:81], v[150:153], v[206:209], v[78:81]
	v_mfma_f32_16x16x32_bf16 v[94:97], v[150:153], v[190:193], v[94:97]
	v_mfma_f32_16x16x32_bf16 v[94:97], v[146:149], v[186:189], v[94:97]
	v_mfma_f32_16x16x32_bf16 v[110:113], v[146:149], v[178:181], v[110:113]
	v_mfma_f32_16x16x32_bf16 v[110:113], v[150:153], v[182:185], v[110:113]
	v_mfma_f32_16x16x32_bf16 v[122:125], v[150:153], v[174:177], v[122:125]
	v_mfma_f32_16x16x32_bf16 v[122:125], v[146:149], v[170:173], v[122:125]
	v_mfma_f32_16x16x32_bf16 v[114:117], v[154:157], v[170:173], v[114:117]
	v_mfma_f32_16x16x32_bf16 v[114:117], v[158:161], v[174:177], v[114:117]
	v_mfma_f32_16x16x32_bf16 v[98:101], v[158:161], v[182:185], v[98:101]
	v_mfma_f32_16x16x32_bf16 v[98:101], v[154:157], v[178:181], v[98:101]
	v_mfma_f32_16x16x32_bf16 v[82:85], v[154:157], v[186:189], v[82:85]
	v_mfma_f32_16x16x32_bf16 v[82:85], v[158:161], v[190:193], v[82:85]
	v_mfma_f32_16x16x32_bf16 v[70:73], v[158:161], v[206:209], v[70:73]
	v_mfma_f32_16x16x32_bf16 v[70:73], v[154:157], v[202:205], v[70:73]
	v_mfma_f32_16x16x32_bf16 v[66:69], v[162:165], v[202:205], v[66:69]
	v_mfma_f32_16x16x32_bf16 v[66:69], v[166:169], v[206:209], v[66:69]
	v_mfma_f32_16x16x32_bf16 v[74:77], v[166:169], v[190:193], v[74:77]
	v_mfma_f32_16x16x32_bf16 v[74:77], v[162:165], v[186:189], v[74:77]
	v_mfma_f32_16x16x32_bf16 v[90:93], v[162:165], v[178:181], v[90:93]
	v_mfma_f32_16x16x32_bf16 v[90:93], v[166:169], v[182:185], v[90:93]
	v_mfma_f32_16x16x32_bf16 v[106:109], v[166:169], v[174:177], v[106:109]
	v_mfma_f32_16x16x32_bf16 v[106:109], v[162:165], v[170:173], v[106:109]
	s_barrier
	s_setprio 0
	s_mov_b32 m0, s70
	v_lshl_add_u64 v[134:135], s[38:39], 0, v[132:133]
	ds_read_b128 v[170:173], v137 offset:16384
	ds_read_b128 v[174:177], v137 offset:17408
	ds_read_b128 v[178:181], v137 offset:18432
	ds_read_b128 v[182:185], v137 offset:19456
	ds_read_b128 v[186:189], v137 offset:20480
	ds_read_b128 v[190:193], v137 offset:21504
	ds_read_b128 v[202:205], v137 offset:22528
	ds_read_b128 v[206:209], v137 offset:23552
	global_load_lds_dwordx4 v[134:135], off
	v_lshl_add_u64 v[210:211], s[38:39], 0, v[130:131]
	s_mov_b32 m0, s67
	v_lshl_add_u64 v[212:213], s[46:47], 0, v[132:133]
	global_load_lds_dwordx4 v[210:211], off
	s_mov_b32 m0, s69
	v_lshl_add_u64 v[214:215], s[36:37], 0, v[130:131]
	global_load_lds_dwordx4 v[212:213], off
	v_lshl_add_u64 v[212:213], s[46:47], 0, v[130:131]
	s_mov_b32 m0, s68
	s_nop 0
	global_load_lds_dwordx4 v[212:213], off
	v_lshl_add_u64 v[212:213], s[36:37], 0, v[132:133]
	s_mov_b32 m0, s53
	s_nop 0
	global_load_lds_dwordx4 v[212:213], off
	s_mov_b32 m0, s56
	s_nop 0
	global_load_lds_dwordx4 v[214:215], off
	s_waitcnt vmcnt(8)
	s_waitcnt lgkmcnt(0)
	.p2align 3
	s_setprio 1
	s_barrier
	v_mfma_f32_16x16x32_bf16 v[62:65], v[138:141], v[170:173], v[62:65]
	v_mfma_f32_16x16x32_bf16 v[62:65], v[142:145], v[174:177], v[62:65]
	v_mfma_f32_16x16x32_bf16 v[54:57], v[142:145], v[182:185], v[54:57]
	v_mfma_f32_16x16x32_bf16 v[54:57], v[138:141], v[178:181], v[54:57]
	v_mfma_f32_16x16x32_bf16 v[38:41], v[138:141], v[186:189], v[38:41]
	v_mfma_f32_16x16x32_bf16 v[38:41], v[142:145], v[190:193], v[38:41]
	v_mfma_f32_16x16x32_bf16 v[22:25], v[142:145], v[206:209], v[22:25]
	v_mfma_f32_16x16x32_bf16 v[22:25], v[138:141], v[202:205], v[22:25]
	v_mfma_f32_16x16x32_bf16 v[14:17], v[146:149], v[202:205], v[14:17]
	v_mfma_f32_16x16x32_bf16 v[14:17], v[150:153], v[206:209], v[14:17]
	v_mfma_f32_16x16x32_bf16 v[30:33], v[150:153], v[190:193], v[30:33]
	v_mfma_f32_16x16x32_bf16 v[30:33], v[146:149], v[186:189], v[30:33]
	v_mfma_f32_16x16x32_bf16 v[46:49], v[146:149], v[178:181], v[46:49]
	v_mfma_f32_16x16x32_bf16 v[46:49], v[150:153], v[182:185], v[46:49]
	v_mfma_f32_16x16x32_bf16 v[58:61], v[150:153], v[174:177], v[58:61]
	v_mfma_f32_16x16x32_bf16 v[58:61], v[146:149], v[170:173], v[58:61]
	v_mfma_f32_16x16x32_bf16 v[50:53], v[154:157], v[170:173], v[50:53]
	v_mfma_f32_16x16x32_bf16 v[50:53], v[158:161], v[174:177], v[50:53]
	v_mfma_f32_16x16x32_bf16 v[34:37], v[158:161], v[182:185], v[34:37]
	v_mfma_f32_16x16x32_bf16 v[34:37], v[154:157], v[178:181], v[34:37]
	v_mfma_f32_16x16x32_bf16 v[18:21], v[154:157], v[186:189], v[18:21]
	v_mfma_f32_16x16x32_bf16 v[18:21], v[158:161], v[190:193], v[18:21]
	v_mfma_f32_16x16x32_bf16 v[6:9], v[158:161], v[206:209], v[6:9]
	v_mfma_f32_16x16x32_bf16 v[6:9], v[154:157], v[202:205], v[6:9]
	v_mfma_f32_16x16x32_bf16 v[2:5], v[162:165], v[202:205], v[2:5]
	v_mfma_f32_16x16x32_bf16 v[2:5], v[166:169], v[206:209], v[2:5]
	v_mfma_f32_16x16x32_bf16 v[10:13], v[166:169], v[190:193], v[10:13]
	v_mfma_f32_16x16x32_bf16 v[10:13], v[162:165], v[186:189], v[10:13]
	v_mfma_f32_16x16x32_bf16 v[26:29], v[162:165], v[178:181], v[26:29]
	v_mfma_f32_16x16x32_bf16 v[26:29], v[166:169], v[182:185], v[26:29]
	v_mfma_f32_16x16x32_bf16 v[42:45], v[166:169], v[174:177], v[42:45]
	v_mfma_f32_16x16x32_bf16 v[42:45], v[162:165], v[170:173], v[42:45]
	s_barrier
	s_setprio 0
	v_add_u32_e32 v150, s66, v136
	v_add_u32_e32 v166, s65, v136
	ds_read_b128 v[138:141], v150
	ds_read_b128 v[142:145], v150 offset:1024
	ds_read_b128 v[146:149], v150 offset:2048
	ds_read_b128 v[150:153], v150 offset:3072
	ds_read_b128 v[154:157], v166
	ds_read_b128 v[158:161], v166 offset:1024
	ds_read_b128 v[162:165], v166 offset:2048
	ds_read_b128 v[166:169], v166 offset:3072
	s_mov_b32 m0, s57
	v_lshl_add_u64 v[216:217], s[30:31], 0, v[132:133]
	ds_read_b128 v[170:173], v137 offset:32768
	ds_read_b128 v[174:177], v137 offset:33792
	ds_read_b128 v[178:181], v137 offset:34816
	ds_read_b128 v[182:185], v137 offset:35840
	ds_read_b128 v[186:189], v137 offset:36864
	ds_read_b128 v[190:193], v137 offset:37888
	ds_read_b128 v[202:205], v137 offset:38912
	ds_read_b128 v[206:209], v137 offset:39936
	global_load_lds_dwordx4 v[216:217], off
	v_lshl_add_u64 v[216:217], s[30:31], 0, v[130:131]
	s_mov_b32 m0, s58
	s_nop 0
	global_load_lds_dwordx4 v[216:217], off
	s_waitcnt vmcnt(8)
	s_waitcnt lgkmcnt(0)
	.p2align 3
	s_setprio 1
	s_barrier
	v_mfma_f32_16x16x32_bf16 v[126:129], v[138:141], v[170:173], v[126:129]
	v_mfma_f32_16x16x32_bf16 v[126:129], v[142:145], v[174:177], v[126:129]
	v_mfma_f32_16x16x32_bf16 v[118:121], v[142:145], v[182:185], v[118:121]
	v_mfma_f32_16x16x32_bf16 v[118:121], v[138:141], v[178:181], v[118:121]
	v_mfma_f32_16x16x32_bf16 v[102:105], v[138:141], v[186:189], v[102:105]
	v_mfma_f32_16x16x32_bf16 v[102:105], v[142:145], v[190:193], v[102:105]
	v_mfma_f32_16x16x32_bf16 v[86:89], v[142:145], v[206:209], v[86:89]
	v_mfma_f32_16x16x32_bf16 v[86:89], v[138:141], v[202:205], v[86:89]
	v_mfma_f32_16x16x32_bf16 v[78:81], v[146:149], v[202:205], v[78:81]
	v_mfma_f32_16x16x32_bf16 v[78:81], v[150:153], v[206:209], v[78:81]
	v_mfma_f32_16x16x32_bf16 v[94:97], v[150:153], v[190:193], v[94:97]
	v_mfma_f32_16x16x32_bf16 v[94:97], v[146:149], v[186:189], v[94:97]
	v_mfma_f32_16x16x32_bf16 v[110:113], v[146:149], v[178:181], v[110:113]
	v_mfma_f32_16x16x32_bf16 v[110:113], v[150:153], v[182:185], v[110:113]
	v_mfma_f32_16x16x32_bf16 v[122:125], v[150:153], v[174:177], v[122:125]
	v_mfma_f32_16x16x32_bf16 v[122:125], v[146:149], v[170:173], v[122:125]
	v_mfma_f32_16x16x32_bf16 v[114:117], v[154:157], v[170:173], v[114:117]
	v_mfma_f32_16x16x32_bf16 v[114:117], v[158:161], v[174:177], v[114:117]
	v_mfma_f32_16x16x32_bf16 v[98:101], v[158:161], v[182:185], v[98:101]
	v_mfma_f32_16x16x32_bf16 v[98:101], v[154:157], v[178:181], v[98:101]
	v_mfma_f32_16x16x32_bf16 v[82:85], v[154:157], v[186:189], v[82:85]
	v_mfma_f32_16x16x32_bf16 v[82:85], v[158:161], v[190:193], v[82:85]
	v_mfma_f32_16x16x32_bf16 v[70:73], v[158:161], v[206:209], v[70:73]
	v_mfma_f32_16x16x32_bf16 v[70:73], v[154:157], v[202:205], v[70:73]
	v_mfma_f32_16x16x32_bf16 v[66:69], v[162:165], v[202:205], v[66:69]
	v_mfma_f32_16x16x32_bf16 v[66:69], v[166:169], v[206:209], v[66:69]
	v_mfma_f32_16x16x32_bf16 v[74:77], v[166:169], v[190:193], v[74:77]
	v_mfma_f32_16x16x32_bf16 v[74:77], v[162:165], v[186:189], v[74:77]
	v_mfma_f32_16x16x32_bf16 v[90:93], v[162:165], v[178:181], v[90:93]
	v_mfma_f32_16x16x32_bf16 v[90:93], v[166:169], v[182:185], v[90:93]
	v_mfma_f32_16x16x32_bf16 v[106:109], v[166:169], v[174:177], v[106:109]
	v_mfma_f32_16x16x32_bf16 v[106:109], v[162:165], v[170:173], v[106:109]
	s_barrier
	s_setprio 0
	s_mov_b32 m0, s64
	v_lshl_add_u64 v[134:135], v[134:135], 0, s[10:11]
	ds_read_b128 v[170:173], v137 offset:49152
	ds_read_b128 v[174:177], v137 offset:50176
	ds_read_b128 v[178:181], v137 offset:51200
	ds_read_b128 v[182:185], v137 offset:52224
	ds_read_b128 v[186:189], v137 offset:53248
	ds_read_b128 v[190:193], v137 offset:54272
	ds_read_b128 v[202:205], v137 offset:55296
	ds_read_b128 v[206:209], v137 offset:56320
	global_load_lds_dwordx4 v[134:135], off
	v_lshl_add_u64 v[134:135], v[210:211], 0, s[10:11]
	s_mov_b32 m0, s21
	s_nop 0
	global_load_lds_dwordx4 v[134:135], off
	v_lshl_add_u64 v[134:135], s[28:29], 0, v[132:133]
	s_mov_b32 m0, s72
	s_nop 0
	global_load_lds_dwordx4 v[134:135], off
	v_lshl_add_u64 v[134:135], s[28:29], 0, v[130:131]
	s_mov_b32 m0, s71
	s_nop 0
	global_load_lds_dwordx4 v[134:135], off
	v_lshl_add_u64 v[134:135], v[212:213], 0, s[10:11]
	s_mov_b32 m0, s59
	s_nop 0
	global_load_lds_dwordx4 v[134:135], off
	v_lshl_add_u64 v[134:135], v[214:215], 0, s[10:11]
	s_mov_b32 m0, s60
	s_nop 0
	global_load_lds_dwordx4 v[134:135], off
	s_waitcnt vmcnt(8)
	s_waitcnt lgkmcnt(0)
	.p2align 3
	s_setprio 1
	s_barrier
	v_mfma_f32_16x16x32_bf16 v[62:65], v[138:141], v[170:173], v[62:65]
	v_mfma_f32_16x16x32_bf16 v[62:65], v[142:145], v[174:177], v[62:65]
	v_mfma_f32_16x16x32_bf16 v[54:57], v[142:145], v[182:185], v[54:57]
	v_mfma_f32_16x16x32_bf16 v[54:57], v[138:141], v[178:181], v[54:57]
	v_mfma_f32_16x16x32_bf16 v[38:41], v[138:141], v[186:189], v[38:41]
	v_mfma_f32_16x16x32_bf16 v[38:41], v[142:145], v[190:193], v[38:41]
	v_mfma_f32_16x16x32_bf16 v[22:25], v[142:145], v[206:209], v[22:25]
	v_mfma_f32_16x16x32_bf16 v[22:25], v[138:141], v[202:205], v[22:25]
	v_mfma_f32_16x16x32_bf16 v[14:17], v[146:149], v[202:205], v[14:17]
	v_mfma_f32_16x16x32_bf16 v[14:17], v[150:153], v[206:209], v[14:17]
	v_mfma_f32_16x16x32_bf16 v[30:33], v[150:153], v[190:193], v[30:33]
	v_mfma_f32_16x16x32_bf16 v[30:33], v[146:149], v[186:189], v[30:33]
	v_mfma_f32_16x16x32_bf16 v[46:49], v[146:149], v[178:181], v[46:49]
	v_mfma_f32_16x16x32_bf16 v[46:49], v[150:153], v[182:185], v[46:49]
	v_mfma_f32_16x16x32_bf16 v[58:61], v[150:153], v[174:177], v[58:61]
	v_mfma_f32_16x16x32_bf16 v[58:61], v[146:149], v[170:173], v[58:61]
	v_mfma_f32_16x16x32_bf16 v[50:53], v[154:157], v[170:173], v[50:53]
	v_mfma_f32_16x16x32_bf16 v[50:53], v[158:161], v[174:177], v[50:53]
	v_mfma_f32_16x16x32_bf16 v[34:37], v[158:161], v[182:185], v[34:37]
	v_mfma_f32_16x16x32_bf16 v[34:37], v[154:157], v[178:181], v[34:37]
	v_mfma_f32_16x16x32_bf16 v[18:21], v[154:157], v[186:189], v[18:21]
	v_mfma_f32_16x16x32_bf16 v[18:21], v[158:161], v[190:193], v[18:21]
	v_mfma_f32_16x16x32_bf16 v[6:9], v[158:161], v[206:209], v[6:9]
	v_mfma_f32_16x16x32_bf16 v[6:9], v[154:157], v[202:205], v[6:9]
	v_mfma_f32_16x16x32_bf16 v[2:5], v[162:165], v[202:205], v[2:5]
	v_mfma_f32_16x16x32_bf16 v[2:5], v[166:169], v[206:209], v[2:5]
	v_mfma_f32_16x16x32_bf16 v[10:13], v[166:169], v[190:193], v[10:13]
	v_mfma_f32_16x16x32_bf16 v[10:13], v[162:165], v[186:189], v[10:13]
	v_mfma_f32_16x16x32_bf16 v[26:29], v[162:165], v[178:181], v[26:29]
	v_mfma_f32_16x16x32_bf16 v[26:29], v[166:169], v[182:185], v[26:29]
	v_mfma_f32_16x16x32_bf16 v[42:45], v[166:169], v[174:177], v[42:45]
	v_mfma_f32_16x16x32_bf16 v[42:45], v[162:165], v[170:173], v[42:45]
	s_barrier
	s_setprio 0
	s_andn2_b64 vcc, exec, s[26:27]
	s_mov_b64 s[28:29], -1
	s_mov_b64 s[26:27], 0
	s_movk_i32 s21, 0x100
	s_cbranch_vccz .LBB0_1002
	s_and_b64 vcc, exec, s[16:17]
	s_cbranch_vccz .LBB0_1005
	s_barrier

.LBB0_1087:
	s_add_u32 s30, s28, 0xfff80080
	s_addc_u32 s31, s29, -1
	s_cmp_eq_u32 s83, 28
	s_cselect_b32 s43, s23, s31
	s_cselect_b32 s42, s44, s30
	s_cselect_b32 s31, s21, s82
	s_cselect_b32 s30, s45, s81
	s_add_i32 s84, 0, 0x10000
	s_add_i32 s86, 0, 0x14000
	v_add_u32_e32 v62, s84, v229
	v_add_u32_e32 v158, s86, v229
	ds_read_b128 v[42:45], v62
	ds_read_b128 v[46:49], v62 offset:1024
	ds_read_b128 v[58:61], v62 offset:2048
	ds_read_b128 v[62:65], v62 offset:3072
	ds_read_b128 v[146:149], v158
	ds_read_b128 v[150:153], v158 offset:1024
	ds_read_b128 v[154:157], v158 offset:2048
	ds_read_b128 v[158:161], v158 offset:3072
	v_lshl_add_u64 v[208:209], s[28:29], 0, v[204:205]
	s_add_i32 m0, s71, 0xc000
	ds_read_b128 v[162:165], v230
	ds_read_b128 v[166:169], v230 offset:1024
	ds_read_b128 v[170:173], v230 offset:2048
	ds_read_b128 v[174:177], v230 offset:3072
	ds_read_b128 v[178:181], v230 offset:4096
	ds_read_b128 v[182:185], v230 offset:5120
	ds_read_b128 v[186:189], v230 offset:6144
	ds_read_b128 v[190:193], v230 offset:7168
	global_load_lds_dwordx4 v[208:209], off
	v_lshl_add_u64 v[208:209], s[28:29], 0, v[206:207]
	s_add_i32 m0, s71, 0xe000
	s_nop 0
	global_load_lds_dwordx4 v[208:209], off
	s_waitcnt vmcnt(8)
	s_waitcnt lgkmcnt(0)
	.p2align 3
	s_setprio 1
	s_barrier
	v_mfma_f32_16x16x32_bf16 v[142:145], v[42:45], v[162:165], v[142:145]
	v_mfma_f32_16x16x32_bf16 v[142:145], v[46:49], v[166:169], v[142:145]
	v_mfma_f32_16x16x32_bf16 v[126:129], v[46:49], v[174:177], v[126:129]
	v_mfma_f32_16x16x32_bf16 v[126:129], v[42:45], v[170:173], v[126:129]
	v_mfma_f32_16x16x32_bf16 v[110:113], v[42:45], v[178:181], v[110:113]
	v_mfma_f32_16x16x32_bf16 v[110:113], v[46:49], v[182:185], v[110:113]
	v_mfma_f32_16x16x32_bf16 v[94:97], v[46:49], v[190:193], v[94:97]
	v_mfma_f32_16x16x32_bf16 v[94:97], v[42:45], v[186:189], v[94:97]
	v_mfma_f32_16x16x32_bf16 v[90:93], v[58:61], v[186:189], v[90:93]
	v_mfma_f32_16x16x32_bf16 v[90:93], v[62:65], v[190:193], v[90:93]
	v_mfma_f32_16x16x32_bf16 v[106:109], v[62:65], v[182:185], v[106:109]
	v_mfma_f32_16x16x32_bf16 v[106:109], v[58:61], v[178:181], v[106:109]
	v_mfma_f32_16x16x32_bf16 v[122:125], v[58:61], v[170:173], v[122:125]
	v_mfma_f32_16x16x32_bf16 v[122:125], v[62:65], v[174:177], v[122:125]
	v_mfma_f32_16x16x32_bf16 v[138:141], v[62:65], v[166:169], v[138:141]
	v_mfma_f32_16x16x32_bf16 v[138:141], v[58:61], v[162:165], v[138:141]
	v_mfma_f32_16x16x32_bf16 v[134:137], v[146:149], v[162:165], v[134:137]
	v_mfma_f32_16x16x32_bf16 v[134:137], v[150:153], v[166:169], v[134:137]
	v_mfma_f32_16x16x32_bf16 v[118:121], v[150:153], v[174:177], v[118:121]
	v_mfma_f32_16x16x32_bf16 v[118:121], v[146:149], v[170:173], v[118:121]
	v_mfma_f32_16x16x32_bf16 v[102:105], v[146:149], v[178:181], v[102:105]
	v_mfma_f32_16x16x32_bf16 v[102:105], v[150:153], v[182:185], v[102:105]
	v_mfma_f32_16x16x32_bf16 v[86:89], v[150:153], v[190:193], v[86:89]
	v_mfma_f32_16x16x32_bf16 v[86:89], v[146:149], v[186:189], v[86:89]
	v_mfma_f32_16x16x32_bf16 v[82:85], v[154:157], v[186:189], v[82:85]
	v_mfma_f32_16x16x32_bf16 v[82:85], v[158:161], v[190:193], v[82:85]
	v_mfma_f32_16x16x32_bf16 v[98:101], v[158:161], v[182:185], v[98:101]
	v_mfma_f32_16x16x32_bf16 v[98:101], v[154:157], v[178:181], v[98:101]
	v_mfma_f32_16x16x32_bf16 v[114:117], v[154:157], v[170:173], v[114:117]
	v_mfma_f32_16x16x32_bf16 v[114:117], v[158:161], v[174:177], v[114:117]
	v_mfma_f32_16x16x32_bf16 v[130:133], v[158:161], v[166:169], v[130:133]
	v_mfma_f32_16x16x32_bf16 v[130:133], v[154:157], v[162:165], v[130:133]
	s_barrier
	s_setprio 0
	s_add_i32 s84, s84, s70
	v_lshl_add_u64 v[208:209], s[30:31], 0, v[194:195]
	s_mov_b32 m0, s84
	ds_read_b128 v[162:165], v230 offset:16384
	ds_read_b128 v[166:169], v230 offset:17408
	ds_read_b128 v[170:173], v230 offset:18432
	ds_read_b128 v[174:177], v230 offset:19456
	ds_read_b128 v[178:181], v230 offset:20480
	ds_read_b128 v[182:185], v230 offset:21504
	ds_read_b128 v[186:189], v230 offset:22528
	ds_read_b128 v[190:193], v230 offset:23552
	global_load_lds_dwordx4 v[208:209], off
	s_add_i32 m0, s84, 0x2000
	s_add_u32 s84, s30, 0x80000
	v_lshl_add_u64 v[210:211], s[30:31], 0, v[202:203]
	s_addc_u32 s85, s31, 0
	s_add_i32 s86, s86, s70
	global_load_lds_dwordx4 v[210:211], off
	v_lshl_add_u64 v[212:213], s[84:85], 0, v[194:195]
	s_mov_b32 m0, s86
	v_lshl_add_u64 v[214:215], s[42:43], 0, v[202:203]
	global_load_lds_dwordx4 v[212:213], off
	v_lshl_add_u64 v[212:213], s[84:85], 0, v[202:203]
	s_add_i32 m0, s86, 0x2000
	s_nop 0
	global_load_lds_dwordx4 v[212:213], off
	v_lshl_add_u64 v[212:213], s[42:43], 0, v[194:195]
	s_mov_b32 m0, s71
	s_nop 0
	global_load_lds_dwordx4 v[212:213], off
	s_mov_b32 m0, s72
	s_nop 0
	global_load_lds_dwordx4 v[214:215], off
	s_waitcnt vmcnt(8)
	s_waitcnt lgkmcnt(0)
	.p2align 3
	s_setprio 1
	s_barrier
	v_mfma_f32_16x16x32_bf16 v[78:81], v[42:45], v[162:165], v[78:81]
	v_mfma_f32_16x16x32_bf16 v[78:81], v[46:49], v[166:169], v[78:81]
	v_mfma_f32_16x16x32_bf16 v[54:57], v[46:49], v[174:177], v[54:57]
	v_mfma_f32_16x16x32_bf16 v[54:57], v[42:45], v[170:173], v[54:57]
	v_mfma_f32_16x16x32_bf16 v[30:33], v[42:45], v[178:181], v[30:33]
	v_mfma_f32_16x16x32_bf16 v[30:33], v[46:49], v[182:185], v[30:33]
	v_mfma_f32_16x16x32_bf16 v[14:17], v[46:49], v[190:193], v[14:17]
	v_mfma_f32_16x16x32_bf16 v[14:17], v[42:45], v[186:189], v[14:17]
	v_mfma_f32_16x16x32_bf16 v[10:13], v[58:61], v[186:189], v[10:13]
	v_mfma_f32_16x16x32_bf16 v[10:13], v[62:65], v[190:193], v[10:13]
	v_mfma_f32_16x16x32_bf16 v[26:29], v[62:65], v[182:185], v[26:29]
	v_mfma_f32_16x16x32_bf16 v[26:29], v[58:61], v[178:181], v[26:29]
	v_mfma_f32_16x16x32_bf16 v[50:53], v[58:61], v[170:173], v[50:53]
	v_mfma_f32_16x16x32_bf16 v[50:53], v[62:65], v[174:177], v[50:53]
	v_mfma_f32_16x16x32_bf16 v[74:77], v[62:65], v[166:169], v[74:77]
	v_mfma_f32_16x16x32_bf16 v[74:77], v[58:61], v[162:165], v[74:77]
	v_mfma_f32_16x16x32_bf16 v[38:41], v[146:149], v[170:173], v[38:41]
	v_mfma_f32_16x16x32_bf16 v[34:37], v[154:157], v[170:173], v[34:37]
	v_mfma_f32_16x16x32_bf16 v[22:25], v[146:149], v[178:181], v[22:25]
	v_mfma_f32_16x16x32_bf16 v[18:21], v[154:157], v[178:181], v[18:21]
	v_mfma_f32_16x16x32_bf16 v[6:9], v[146:149], v[186:189], v[6:9]
	v_mfma_f32_16x16x32_bf16 v[2:5], v[154:157], v[186:189], v[2:5]
	v_mfma_f32_16x16x32_bf16 v[42:45], v[146:149], v[162:165], v[70:73]
	v_mfma_f32_16x16x32_bf16 v[46:49], v[154:157], v[162:165], v[66:69]
	v_mfma_f32_16x16x32_bf16 v[38:41], v[150:153], v[174:177], v[38:41]
	v_mfma_f32_16x16x32_bf16 v[34:37], v[158:161], v[174:177], v[34:37]
	v_mfma_f32_16x16x32_bf16 v[22:25], v[150:153], v[182:185], v[22:25]
	v_mfma_f32_16x16x32_bf16 v[18:21], v[158:161], v[182:185], v[18:21]
	v_mfma_f32_16x16x32_bf16 v[6:9], v[150:153], v[190:193], v[6:9]
	v_mfma_f32_16x16x32_bf16 v[2:5], v[158:161], v[190:193], v[2:5]
	v_mfma_f32_16x16x32_bf16 v[42:45], v[150:153], v[166:169], v[42:45]
	v_mfma_f32_16x16x32_bf16 v[46:49], v[158:161], v[166:169], v[46:49]
	s_barrier
	s_setprio 0
	s_add_i32 s84, 0, 0x18000
	s_add_i32 s85, 0, 0x1c000
	v_add_u32_e32 v70, s84, v229
	v_add_u32_e32 v158, s85, v229
	ds_read_b128 v[58:61], v70
	ds_read_b128 v[62:65], v70 offset:1024
	ds_read_b128 v[66:69], v70 offset:2048
	ds_read_b128 v[70:73], v70 offset:3072
	ds_read_b128 v[146:149], v158
	ds_read_b128 v[150:153], v158 offset:1024
	ds_read_b128 v[154:157], v158 offset:2048
	ds_read_b128 v[158:161], v158 offset:3072
	s_add_u32 s42, s42, 0x80000
	s_addc_u32 s43, s43, 0
	s_mov_b32 m0, s73
	v_lshl_add_u64 v[216:217], s[42:43], 0, v[194:195]
	ds_read_b128 v[162:165], v230 offset:32768
	ds_read_b128 v[166:169], v230 offset:33792
	ds_read_b128 v[170:173], v230 offset:34816
	ds_read_b128 v[174:177], v230 offset:35840
	ds_read_b128 v[178:181], v230 offset:36864
	ds_read_b128 v[182:185], v230 offset:37888
	ds_read_b128 v[186:189], v230 offset:38912
	ds_read_b128 v[190:193], v230 offset:39936
	global_load_lds_dwordx4 v[216:217], off
	v_lshl_add_u64 v[216:217], s[42:43], 0, v[202:203]
	s_mov_b32 m0, s74
	s_nop 0
	global_load_lds_dwordx4 v[216:217], off
	s_waitcnt vmcnt(8)
	s_waitcnt lgkmcnt(0)
	.p2align 3
	s_setprio 1
	s_barrier
	v_mfma_f32_16x16x32_bf16 v[142:145], v[58:61], v[162:165], v[142:145]
	v_mfma_f32_16x16x32_bf16 v[142:145], v[62:65], v[166:169], v[142:145]
	v_mfma_f32_16x16x32_bf16 v[126:129], v[62:65], v[174:177], v[126:129]
	v_mfma_f32_16x16x32_bf16 v[126:129], v[58:61], v[170:173], v[126:129]
	v_mfma_f32_16x16x32_bf16 v[110:113], v[58:61], v[178:181], v[110:113]
	v_mfma_f32_16x16x32_bf16 v[110:113], v[62:65], v[182:185], v[110:113]
	v_mfma_f32_16x16x32_bf16 v[94:97], v[62:65], v[190:193], v[94:97]
	v_mfma_f32_16x16x32_bf16 v[94:97], v[58:61], v[186:189], v[94:97]
	v_mfma_f32_16x16x32_bf16 v[90:93], v[66:69], v[186:189], v[90:93]
	v_mfma_f32_16x16x32_bf16 v[90:93], v[70:73], v[190:193], v[90:93]
	v_mfma_f32_16x16x32_bf16 v[106:109], v[70:73], v[182:185], v[106:109]
	v_mfma_f32_16x16x32_bf16 v[106:109], v[66:69], v[178:181], v[106:109]
	v_mfma_f32_16x16x32_bf16 v[122:125], v[66:69], v[170:173], v[122:125]
	v_mfma_f32_16x16x32_bf16 v[122:125], v[70:73], v[174:177], v[122:125]
	v_mfma_f32_16x16x32_bf16 v[138:141], v[70:73], v[166:169], v[138:141]
	v_mfma_f32_16x16x32_bf16 v[138:141], v[66:69], v[162:165], v[138:141]
	v_mfma_f32_16x16x32_bf16 v[134:137], v[146:149], v[162:165], v[134:137]
	v_mfma_f32_16x16x32_bf16 v[134:137], v[150:153], v[166:169], v[134:137]
	v_mfma_f32_16x16x32_bf16 v[118:121], v[150:153], v[174:177], v[118:121]
	v_mfma_f32_16x16x32_bf16 v[118:121], v[146:149], v[170:173], v[118:121]
	v_mfma_f32_16x16x32_bf16 v[102:105], v[146:149], v[178:181], v[102:105]
	v_mfma_f32_16x16x32_bf16 v[102:105], v[150:153], v[182:185], v[102:105]
	v_mfma_f32_16x16x32_bf16 v[86:89], v[150:153], v[190:193], v[86:89]
	v_mfma_f32_16x16x32_bf16 v[86:89], v[146:149], v[186:189], v[86:89]
	v_mfma_f32_16x16x32_bf16 v[82:85], v[154:157], v[186:189], v[82:85]
	v_mfma_f32_16x16x32_bf16 v[82:85], v[158:161], v[190:193], v[82:85]
	v_mfma_f32_16x16x32_bf16 v[98:101], v[158:161], v[182:185], v[98:101]
	v_mfma_f32_16x16x32_bf16 v[98:101], v[154:157], v[178:181], v[98:101]
	v_mfma_f32_16x16x32_bf16 v[114:117], v[154:157], v[170:173], v[114:117]
	v_mfma_f32_16x16x32_bf16 v[114:117], v[158:161], v[174:177], v[114:117]
	v_mfma_f32_16x16x32_bf16 v[130:133], v[158:161], v[166:169], v[130:133]
	v_mfma_f32_16x16x32_bf16 v[130:133], v[154:157], v[162:165], v[130:133]
	s_barrier
	s_setprio 0
	s_add_i32 s42, s84, s70
	v_lshl_add_u64 v[208:209], v[208:209], 0, s[10:11]
	s_mov_b32 m0, s42
	ds_read_b128 v[162:165], v230 offset:49152
	ds_read_b128 v[166:169], v230 offset:50176
	ds_read_b128 v[170:173], v230 offset:51200
	ds_read_b128 v[174:177], v230 offset:52224
	ds_read_b128 v[178:181], v230 offset:53248
	ds_read_b128 v[182:185], v230 offset:54272
	ds_read_b128 v[186:189], v230 offset:55296
	ds_read_b128 v[190:193], v230 offset:56320
	global_load_lds_dwordx4 v[208:209], off
	s_add_i32 m0, s42, 0x2000
	s_add_u32 s30, s30, 0x80080
	v_lshl_add_u64 v[208:209], v[210:211], 0, s[10:11]
	s_addc_u32 s31, s31, 0
	s_add_i32 s42, s85, s70
	global_load_lds_dwordx4 v[208:209], off
	v_lshl_add_u64 v[208:209], s[30:31], 0, v[194:195]
	s_mov_b32 m0, s42
	s_nop 0
	global_load_lds_dwordx4 v[208:209], off
	v_lshl_add_u64 v[208:209], s[30:31], 0, v[202:203]
	s_add_i32 m0, s42, 0x2000
	s_nop 0
	global_load_lds_dwordx4 v[208:209], off
	v_lshl_add_u64 v[208:209], v[212:213], 0, s[10:11]
	s_mov_b32 m0, s79
	s_nop 0
	global_load_lds_dwordx4 v[208:209], off
	v_lshl_add_u64 v[208:209], v[214:215], 0, s[10:11]
	s_mov_b32 m0, s80
	s_nop 0
	global_load_lds_dwordx4 v[208:209], off
	s_waitcnt vmcnt(8)
	s_waitcnt lgkmcnt(0)
	.p2align 3
	s_setprio 1
	s_barrier
	v_mfma_f32_16x16x32_bf16 v[78:81], v[58:61], v[162:165], v[78:81]
	v_mfma_f32_16x16x32_bf16 v[78:81], v[62:65], v[166:169], v[78:81]
	v_mfma_f32_16x16x32_bf16 v[54:57], v[62:65], v[174:177], v[54:57]
	v_mfma_f32_16x16x32_bf16 v[54:57], v[58:61], v[170:173], v[54:57]
	v_mfma_f32_16x16x32_bf16 v[30:33], v[58:61], v[178:181], v[30:33]
	v_mfma_f32_16x16x32_bf16 v[30:33], v[62:65], v[182:185], v[30:33]
	v_mfma_f32_16x16x32_bf16 v[14:17], v[62:65], v[190:193], v[14:17]
	v_mfma_f32_16x16x32_bf16 v[14:17], v[58:61], v[186:189], v[14:17]
	v_mfma_f32_16x16x32_bf16 v[10:13], v[66:69], v[186:189], v[10:13]
	v_mfma_f32_16x16x32_bf16 v[10:13], v[70:73], v[190:193], v[10:13]
	v_mfma_f32_16x16x32_bf16 v[26:29], v[70:73], v[182:185], v[26:29]
	v_mfma_f32_16x16x32_bf16 v[26:29], v[66:69], v[178:181], v[26:29]
	v_mfma_f32_16x16x32_bf16 v[50:53], v[66:69], v[170:173], v[50:53]
	v_mfma_f32_16x16x32_bf16 v[50:53], v[70:73], v[174:177], v[50:53]
	v_mfma_f32_16x16x32_bf16 v[74:77], v[70:73], v[166:169], v[74:77]
	v_mfma_f32_16x16x32_bf16 v[74:77], v[66:69], v[162:165], v[74:77]
	v_mfma_f32_16x16x32_bf16 v[42:45], v[146:149], v[162:165], v[42:45]
	v_mfma_f32_16x16x32_bf16 v[70:73], v[150:153], v[166:169], v[42:45]
	v_mfma_f32_16x16x32_bf16 v[42:45], v[154:157], v[162:165], v[46:49]
	v_mfma_f32_16x16x32_bf16 v[38:41], v[146:149], v[170:173], v[38:41]
	v_mfma_f32_16x16x32_bf16 v[34:37], v[154:157], v[170:173], v[34:37]
	v_mfma_f32_16x16x32_bf16 v[22:25], v[146:149], v[178:181], v[22:25]
	v_mfma_f32_16x16x32_bf16 v[18:21], v[154:157], v[178:181], v[18:21]
	v_mfma_f32_16x16x32_bf16 v[6:9], v[146:149], v[186:189], v[6:9]
	v_mfma_f32_16x16x32_bf16 v[2:5], v[154:157], v[186:189], v[2:5]
	v_mfma_f32_16x16x32_bf16 v[66:69], v[158:161], v[166:169], v[42:45]
	v_mfma_f32_16x16x32_bf16 v[38:41], v[150:153], v[174:177], v[38:41]
	v_mfma_f32_16x16x32_bf16 v[34:37], v[158:161], v[174:177], v[34:37]
	v_mfma_f32_16x16x32_bf16 v[22:25], v[150:153], v[182:185], v[22:25]
	v_mfma_f32_16x16x32_bf16 v[18:21], v[158:161], v[182:185], v[18:21]
	v_mfma_f32_16x16x32_bf16 v[6:9], v[150:153], v[190:193], v[6:9]
	v_mfma_f32_16x16x32_bf16 v[2:5], v[158:161], v[190:193], v[2:5]
	s_barrier
	s_setprio 0
	s_add_i32 s83, s83, 2
	s_add_u32 s28, s28, 0x100
	s_addc_u32 s29, s29, 0
	s_add_u32 s81, s81, 0x100
	s_addc_u32 s82, s82, 0
	s_cmp_gt_u32 s83, 29
	s_cbranch_scc0 .LBB0_1087
	s_and_b64 vcc, exec, s[16:17]
	s_cbranch_vccz .LBB0_1090
	s_barrier

.LBB0_1272:
	s_add_u32 s30, s28, 0xfff80080
	s_addc_u32 s31, s29, -1
	s_add_i32 s66, 0, 0x10000
	s_cmp_eq_u32 s65, 28
	s_cselect_b32 s37, s60, s31
	s_cselect_b32 s36, s61, s30
	s_cselect_b32 s31, s21, s64
	s_cselect_b32 s30, s62, s63
	s_add_i32 s68, 0, 0x14000
	v_add_u32_e32 v126, s66, v156
	v_add_u32_e32 v154, s68, v156
	ds_read_b128 v[114:117], v126
	ds_read_b128 v[118:121], v126 offset:1024
	ds_read_b128 v[122:125], v126 offset:2048
	ds_read_b128 v[126:129], v126 offset:3072
	ds_read_b128 v[158:161], v154
	ds_read_b128 v[162:165], v154 offset:1024
	ds_read_b128 v[166:169], v154 offset:2048
	ds_read_b128 v[170:173], v154 offset:3072
	v_lshl_add_u64 v[154:155], s[28:29], 0, v[150:151]
	s_add_i32 m0, s49, 0xc000
	ds_read_b128 v[174:177], v157
	ds_read_b128 v[178:181], v157 offset:1024
	ds_read_b128 v[182:185], v157 offset:2048
	ds_read_b128 v[186:189], v157 offset:3072
	ds_read_b128 v[190:193], v157 offset:4096
	ds_read_b128 v[202:205], v157 offset:5120
	ds_read_b128 v[206:209], v157 offset:6144
	ds_read_b128 v[210:213], v157 offset:7168
	global_load_lds_dwordx4 v[154:155], off
	v_lshl_add_u64 v[154:155], s[28:29], 0, v[152:153]
	s_add_i32 m0, s49, 0xe000
	s_nop 0
	global_load_lds_dwordx4 v[154:155], off
	s_waitcnt vmcnt(8)
	s_waitcnt lgkmcnt(0)
	.p2align 3
	s_setprio 1
	s_barrier
	v_mfma_f32_16x16x32_bf16 v[142:145], v[114:117], v[174:177], v[142:145]
	v_mfma_f32_16x16x32_bf16 v[142:145], v[118:121], v[178:181], v[142:145]
	v_mfma_f32_16x16x32_bf16 v[110:113], v[118:121], v[186:189], v[110:113]
	v_mfma_f32_16x16x32_bf16 v[110:113], v[114:117], v[182:185], v[110:113]
	v_mfma_f32_16x16x32_bf16 v[94:97], v[114:117], v[190:193], v[94:97]
	v_mfma_f32_16x16x32_bf16 v[94:97], v[118:121], v[202:205], v[94:97]
	v_mfma_f32_16x16x32_bf16 v[78:81], v[118:121], v[210:213], v[78:81]
	v_mfma_f32_16x16x32_bf16 v[78:81], v[114:117], v[206:209], v[78:81]
	v_mfma_f32_16x16x32_bf16 v[74:77], v[122:125], v[206:209], v[74:77]
	v_mfma_f32_16x16x32_bf16 v[74:77], v[126:129], v[210:213], v[74:77]
	v_mfma_f32_16x16x32_bf16 v[90:93], v[126:129], v[202:205], v[90:93]
	v_mfma_f32_16x16x32_bf16 v[90:93], v[122:125], v[190:193], v[90:93]
	v_mfma_f32_16x16x32_bf16 v[106:109], v[122:125], v[182:185], v[106:109]
	v_mfma_f32_16x16x32_bf16 v[106:109], v[126:129], v[186:189], v[106:109]
	v_mfma_f32_16x16x32_bf16 v[138:141], v[126:129], v[178:181], v[138:141]
	v_mfma_f32_16x16x32_bf16 v[138:141], v[122:125], v[174:177], v[138:141]
	v_mfma_f32_16x16x32_bf16 v[134:137], v[158:161], v[174:177], v[134:137]
	v_mfma_f32_16x16x32_bf16 v[134:137], v[162:165], v[178:181], v[134:137]
	v_mfma_f32_16x16x32_bf16 v[102:105], v[162:165], v[186:189], v[102:105]
	v_mfma_f32_16x16x32_bf16 v[102:105], v[158:161], v[182:185], v[102:105]
	v_mfma_f32_16x16x32_bf16 v[86:89], v[158:161], v[190:193], v[86:89]
	v_mfma_f32_16x16x32_bf16 v[86:89], v[162:165], v[202:205], v[86:89]
	v_mfma_f32_16x16x32_bf16 v[70:73], v[162:165], v[210:213], v[70:73]
	v_mfma_f32_16x16x32_bf16 v[70:73], v[158:161], v[206:209], v[70:73]
	v_mfma_f32_16x16x32_bf16 v[66:69], v[166:169], v[206:209], v[66:69]
	v_mfma_f32_16x16x32_bf16 v[66:69], v[170:173], v[210:213], v[66:69]
	v_mfma_f32_16x16x32_bf16 v[82:85], v[170:173], v[202:205], v[82:85]
	v_mfma_f32_16x16x32_bf16 v[82:85], v[166:169], v[190:193], v[82:85]
	v_mfma_f32_16x16x32_bf16 v[98:101], v[166:169], v[182:185], v[98:101]
	v_mfma_f32_16x16x32_bf16 v[98:101], v[170:173], v[186:189], v[98:101]
	v_mfma_f32_16x16x32_bf16 v[130:133], v[170:173], v[178:181], v[130:133]
	v_mfma_f32_16x16x32_bf16 v[130:133], v[166:169], v[174:177], v[130:133]
	s_barrier
	s_setprio 0
	s_add_i32 s66, s66, s48
	v_lshl_add_u64 v[154:155], s[30:31], 0, v[146:147]
	s_mov_b32 m0, s66
	ds_read_b128 v[174:177], v157 offset:16384
	ds_read_b128 v[178:181], v157 offset:17408
	ds_read_b128 v[182:185], v157 offset:18432
	ds_read_b128 v[186:189], v157 offset:19456
	ds_read_b128 v[190:193], v157 offset:20480
	ds_read_b128 v[202:205], v157 offset:21504
	ds_read_b128 v[206:209], v157 offset:22528
	ds_read_b128 v[210:213], v157 offset:23552
	global_load_lds_dwordx4 v[154:155], off
	s_add_i32 m0, s66, 0x2000
	s_add_u32 s66, s30, 0x80000
	v_lshl_add_u64 v[214:215], s[30:31], 0, v[148:149]
	s_addc_u32 s67, s31, 0
	s_add_i32 s68, s68, s48
	global_load_lds_dwordx4 v[214:215], off
	v_lshl_add_u64 v[216:217], s[66:67], 0, v[146:147]
	s_mov_b32 m0, s68
	v_lshl_add_u64 v[228:229], s[36:37], 0, v[148:149]
	global_load_lds_dwordx4 v[216:217], off
	v_lshl_add_u64 v[216:217], s[66:67], 0, v[148:149]
	s_add_i32 m0, s68, 0x2000
	s_nop 0
	global_load_lds_dwordx4 v[216:217], off
	v_lshl_add_u64 v[216:217], s[36:37], 0, v[146:147]
	s_mov_b32 m0, s49
	s_nop 0
	global_load_lds_dwordx4 v[216:217], off
	s_mov_b32 m0, s50
	s_nop 0
	global_load_lds_dwordx4 v[228:229], off
	s_waitcnt vmcnt(8)
	s_waitcnt lgkmcnt(0)
	.p2align 3
	s_setprio 1
	s_barrier
	v_mfma_f32_16x16x32_bf16 v[62:65], v[114:117], v[174:177], v[62:65]
	v_mfma_f32_16x16x32_bf16 v[62:65], v[118:121], v[178:181], v[62:65]
	v_mfma_f32_16x16x32_bf16 v[46:49], v[118:121], v[186:189], v[46:49]
	v_mfma_f32_16x16x32_bf16 v[46:49], v[114:117], v[182:185], v[46:49]
	v_mfma_f32_16x16x32_bf16 v[30:33], v[114:117], v[190:193], v[30:33]
	v_mfma_f32_16x16x32_bf16 v[30:33], v[118:121], v[202:205], v[30:33]
	v_mfma_f32_16x16x32_bf16 v[14:17], v[118:121], v[210:213], v[14:17]
	v_mfma_f32_16x16x32_bf16 v[14:17], v[114:117], v[206:209], v[14:17]
	v_mfma_f32_16x16x32_bf16 v[10:13], v[122:125], v[206:209], v[10:13]
	v_mfma_f32_16x16x32_bf16 v[10:13], v[126:129], v[210:213], v[10:13]
	v_mfma_f32_16x16x32_bf16 v[26:29], v[126:129], v[202:205], v[26:29]
	v_mfma_f32_16x16x32_bf16 v[26:29], v[122:125], v[190:193], v[26:29]
	v_mfma_f32_16x16x32_bf16 v[42:45], v[122:125], v[182:185], v[42:45]
	v_mfma_f32_16x16x32_bf16 v[42:45], v[126:129], v[186:189], v[42:45]
	v_mfma_f32_16x16x32_bf16 v[58:61], v[126:129], v[178:181], v[58:61]
	v_mfma_f32_16x16x32_bf16 v[58:61], v[122:125], v[174:177], v[58:61]
	v_mfma_f32_16x16x32_bf16 v[54:57], v[158:161], v[174:177], v[54:57]
	v_mfma_f32_16x16x32_bf16 v[54:57], v[162:165], v[178:181], v[54:57]
	v_mfma_f32_16x16x32_bf16 v[38:41], v[162:165], v[186:189], v[38:41]
	v_mfma_f32_16x16x32_bf16 v[38:41], v[158:161], v[182:185], v[38:41]
	v_mfma_f32_16x16x32_bf16 v[22:25], v[158:161], v[190:193], v[22:25]
	v_mfma_f32_16x16x32_bf16 v[22:25], v[162:165], v[202:205], v[22:25]
	v_mfma_f32_16x16x32_bf16 v[6:9], v[162:165], v[210:213], v[6:9]
	v_mfma_f32_16x16x32_bf16 v[6:9], v[158:161], v[206:209], v[6:9]
	v_mfma_f32_16x16x32_bf16 v[2:5], v[166:169], v[206:209], v[2:5]
	v_mfma_f32_16x16x32_bf16 v[2:5], v[170:173], v[210:213], v[2:5]
	v_mfma_f32_16x16x32_bf16 v[18:21], v[170:173], v[202:205], v[18:21]
	v_mfma_f32_16x16x32_bf16 v[18:21], v[166:169], v[190:193], v[18:21]
	v_mfma_f32_16x16x32_bf16 v[34:37], v[166:169], v[182:185], v[34:37]
	v_mfma_f32_16x16x32_bf16 v[34:37], v[170:173], v[186:189], v[34:37]
	v_mfma_f32_16x16x32_bf16 v[50:53], v[170:173], v[178:181], v[50:53]
	v_mfma_f32_16x16x32_bf16 v[50:53], v[166:169], v[174:177], v[50:53]
	s_barrier
	s_setprio 0
	s_add_i32 s66, 0, 0x18000
	s_add_i32 s67, 0, 0x1c000
	v_add_u32_e32 v126, s66, v156
	v_add_u32_e32 v170, s67, v156
	ds_read_b128 v[114:117], v126
	ds_read_b128 v[118:121], v126 offset:1024
	ds_read_b128 v[122:125], v126 offset:2048
	ds_read_b128 v[126:129], v126 offset:3072
	ds_read_b128 v[158:161], v170
	ds_read_b128 v[162:165], v170 offset:1024
	ds_read_b128 v[166:169], v170 offset:2048
	ds_read_b128 v[170:173], v170 offset:3072
	s_add_u32 s36, s36, 0x80000
	s_addc_u32 s37, s37, 0
	s_mov_b32 m0, s51
	v_lshl_add_u64 v[230:231], s[36:37], 0, v[146:147]
	ds_read_b128 v[174:177], v157 offset:32768
	ds_read_b128 v[178:181], v157 offset:33792
	ds_read_b128 v[182:185], v157 offset:34816
	ds_read_b128 v[186:189], v157 offset:35840
	ds_read_b128 v[190:193], v157 offset:36864
	ds_read_b128 v[202:205], v157 offset:37888
	ds_read_b128 v[206:209], v157 offset:38912
	ds_read_b128 v[210:213], v157 offset:39936
	global_load_lds_dwordx4 v[230:231], off
	v_lshl_add_u64 v[230:231], s[36:37], 0, v[148:149]
	s_mov_b32 m0, s52
	s_nop 0
	global_load_lds_dwordx4 v[230:231], off
	s_waitcnt vmcnt(8)
	s_waitcnt lgkmcnt(0)
	.p2align 3
	s_setprio 1
	s_barrier
	v_mfma_f32_16x16x32_bf16 v[142:145], v[114:117], v[174:177], v[142:145]
	v_mfma_f32_16x16x32_bf16 v[142:145], v[118:121], v[178:181], v[142:145]
	v_mfma_f32_16x16x32_bf16 v[110:113], v[118:121], v[186:189], v[110:113]
	v_mfma_f32_16x16x32_bf16 v[110:113], v[114:117], v[182:185], v[110:113]
	v_mfma_f32_16x16x32_bf16 v[94:97], v[114:117], v[190:193], v[94:97]
	v_mfma_f32_16x16x32_bf16 v[94:97], v[118:121], v[202:205], v[94:97]
	v_mfma_f32_16x16x32_bf16 v[78:81], v[118:121], v[210:213], v[78:81]
	v_mfma_f32_16x16x32_bf16 v[78:81], v[114:117], v[206:209], v[78:81]
	v_mfma_f32_16x16x32_bf16 v[74:77], v[122:125], v[206:209], v[74:77]
	v_mfma_f32_16x16x32_bf16 v[74:77], v[126:129], v[210:213], v[74:77]
	v_mfma_f32_16x16x32_bf16 v[90:93], v[126:129], v[202:205], v[90:93]
	v_mfma_f32_16x16x32_bf16 v[90:93], v[122:125], v[190:193], v[90:93]
	v_mfma_f32_16x16x32_bf16 v[106:109], v[122:125], v[182:185], v[106:109]
	v_mfma_f32_16x16x32_bf16 v[106:109], v[126:129], v[186:189], v[106:109]
	v_mfma_f32_16x16x32_bf16 v[138:141], v[126:129], v[178:181], v[138:141]
	v_mfma_f32_16x16x32_bf16 v[138:141], v[122:125], v[174:177], v[138:141]
	v_mfma_f32_16x16x32_bf16 v[134:137], v[158:161], v[174:177], v[134:137]
	v_mfma_f32_16x16x32_bf16 v[134:137], v[162:165], v[178:181], v[134:137]
	v_mfma_f32_16x16x32_bf16 v[102:105], v[162:165], v[186:189], v[102:105]
	v_mfma_f32_16x16x32_bf16 v[102:105], v[158:161], v[182:185], v[102:105]
	v_mfma_f32_16x16x32_bf16 v[86:89], v[158:161], v[190:193], v[86:89]
	v_mfma_f32_16x16x32_bf16 v[86:89], v[162:165], v[202:205], v[86:89]
	v_mfma_f32_16x16x32_bf16 v[70:73], v[162:165], v[210:213], v[70:73]
	v_mfma_f32_16x16x32_bf16 v[70:73], v[158:161], v[206:209], v[70:73]
	v_mfma_f32_16x16x32_bf16 v[66:69], v[166:169], v[206:209], v[66:69]
	v_mfma_f32_16x16x32_bf16 v[66:69], v[170:173], v[210:213], v[66:69]
	v_mfma_f32_16x16x32_bf16 v[82:85], v[170:173], v[202:205], v[82:85]
	v_mfma_f32_16x16x32_bf16 v[82:85], v[166:169], v[190:193], v[82:85]
	v_mfma_f32_16x16x32_bf16 v[98:101], v[166:169], v[182:185], v[98:101]
	v_mfma_f32_16x16x32_bf16 v[98:101], v[170:173], v[186:189], v[98:101]
	v_mfma_f32_16x16x32_bf16 v[130:133], v[170:173], v[178:181], v[130:133]
	v_mfma_f32_16x16x32_bf16 v[130:133], v[166:169], v[174:177], v[130:133]
	s_barrier
	s_setprio 0
	s_add_i32 s36, s66, s48
	v_lshl_add_u64 v[154:155], v[154:155], 0, s[10:11]
	s_mov_b32 m0, s36
	ds_read_b128 v[174:177], v157 offset:49152
	ds_read_b128 v[178:181], v157 offset:50176
	ds_read_b128 v[182:185], v157 offset:51200
	ds_read_b128 v[186:189], v157 offset:52224
	ds_read_b128 v[190:193], v157 offset:53248
	ds_read_b128 v[202:205], v157 offset:54272
	ds_read_b128 v[206:209], v157 offset:55296
	ds_read_b128 v[210:213], v157 offset:56320
	global_load_lds_dwordx4 v[154:155], off
	s_add_i32 m0, s36, 0x2000
	s_add_u32 s30, s30, 0x80080
	v_lshl_add_u64 v[154:155], v[214:215], 0, s[10:11]
	s_addc_u32 s31, s31, 0
	s_add_i32 s36, s67, s48
	global_load_lds_dwordx4 v[154:155], off
	v_lshl_add_u64 v[154:155], s[30:31], 0, v[146:147]
	s_mov_b32 m0, s36
	s_nop 0
	global_load_lds_dwordx4 v[154:155], off
	v_lshl_add_u64 v[154:155], s[30:31], 0, v[148:149]
	s_add_i32 m0, s36, 0x2000
	s_nop 0
	global_load_lds_dwordx4 v[154:155], off
	v_lshl_add_u64 v[154:155], v[216:217], 0, s[10:11]
	s_mov_b32 m0, s53
	s_nop 0
	global_load_lds_dwordx4 v[154:155], off
	v_lshl_add_u64 v[154:155], v[228:229], 0, s[10:11]
	s_mov_b32 m0, s56
	s_nop 0
	global_load_lds_dwordx4 v[154:155], off
	s_waitcnt vmcnt(8)
	s_waitcnt lgkmcnt(0)
	.p2align 3
	s_setprio 1
	s_barrier
	v_mfma_f32_16x16x32_bf16 v[62:65], v[114:117], v[174:177], v[62:65]
	v_mfma_f32_16x16x32_bf16 v[62:65], v[118:121], v[178:181], v[62:65]
	v_mfma_f32_16x16x32_bf16 v[46:49], v[118:121], v[186:189], v[46:49]
	v_mfma_f32_16x16x32_bf16 v[46:49], v[114:117], v[182:185], v[46:49]
	v_mfma_f32_16x16x32_bf16 v[30:33], v[114:117], v[190:193], v[30:33]
	v_mfma_f32_16x16x32_bf16 v[30:33], v[118:121], v[202:205], v[30:33]
	v_mfma_f32_16x16x32_bf16 v[14:17], v[118:121], v[210:213], v[14:17]
	v_mfma_f32_16x16x32_bf16 v[14:17], v[114:117], v[206:209], v[14:17]
	v_mfma_f32_16x16x32_bf16 v[10:13], v[122:125], v[206:209], v[10:13]
	v_mfma_f32_16x16x32_bf16 v[10:13], v[126:129], v[210:213], v[10:13]
	v_mfma_f32_16x16x32_bf16 v[26:29], v[126:129], v[202:205], v[26:29]
	v_mfma_f32_16x16x32_bf16 v[26:29], v[122:125], v[190:193], v[26:29]
	v_mfma_f32_16x16x32_bf16 v[42:45], v[122:125], v[182:185], v[42:45]
	v_mfma_f32_16x16x32_bf16 v[42:45], v[126:129], v[186:189], v[42:45]
	v_mfma_f32_16x16x32_bf16 v[58:61], v[126:129], v[178:181], v[58:61]
	v_mfma_f32_16x16x32_bf16 v[58:61], v[122:125], v[174:177], v[58:61]
	v_mfma_f32_16x16x32_bf16 v[54:57], v[158:161], v[174:177], v[54:57]
	v_mfma_f32_16x16x32_bf16 v[54:57], v[162:165], v[178:181], v[54:57]
	v_mfma_f32_16x16x32_bf16 v[38:41], v[162:165], v[186:189], v[38:41]
	v_mfma_f32_16x16x32_bf16 v[38:41], v[158:161], v[182:185], v[38:41]
	v_mfma_f32_16x16x32_bf16 v[22:25], v[158:161], v[190:193], v[22:25]
	v_mfma_f32_16x16x32_bf16 v[22:25], v[162:165], v[202:205], v[22:25]
	v_mfma_f32_16x16x32_bf16 v[6:9], v[162:165], v[210:213], v[6:9]
	v_mfma_f32_16x16x32_bf16 v[6:9], v[158:161], v[206:209], v[6:9]
	v_mfma_f32_16x16x32_bf16 v[2:5], v[166:169], v[206:209], v[2:5]
	v_mfma_f32_16x16x32_bf16 v[2:5], v[170:173], v[210:213], v[2:5]
	v_mfma_f32_16x16x32_bf16 v[18:21], v[170:173], v[202:205], v[18:21]
	v_mfma_f32_16x16x32_bf16 v[18:21], v[166:169], v[190:193], v[18:21]
	v_mfma_f32_16x16x32_bf16 v[34:37], v[166:169], v[182:185], v[34:37]
	v_mfma_f32_16x16x32_bf16 v[34:37], v[170:173], v[186:189], v[34:37]
	v_mfma_f32_16x16x32_bf16 v[50:53], v[170:173], v[178:181], v[50:53]
	v_mfma_f32_16x16x32_bf16 v[50:53], v[166:169], v[174:177], v[50:53]
	s_barrier
	s_setprio 0
	s_add_i32 s65, s65, 2
	s_add_u32 s28, s28, 0x100
	s_addc_u32 s29, s29, 0
	s_add_u32 s63, s63, 0x100
	s_addc_u32 s64, s64, 0
	s_cmp_gt_u32 s65, 29
	s_cbranch_scc0 .LBB0_1272
	s_and_b64 vcc, exec, s[18:19]
	s_cbranch_vccz .LBB0_1275
	s_barrier

.LBB0_1346:
	s_or_b32 s20, s30, 1
	s_mul_hi_u32 s31, s20, 0x280000
	s_mul_i32 s42, s20, 0x280000
	s_add_u32 s20, s56, s18
	s_addc_u32 s21, s57, s19
	s_add_u32 s18, s16, 0x280000
	s_addc_u32 s19, s17, 0
	s_add_i32 s44, 0, 0x10000
	s_add_i32 s45, 0, 0x14000
	v_add_u32_e32 v146, s44, v44
	v_add_u32_e32 v162, s45, v44
	ds_read_b128 v[46:49], v146
	ds_read_b128 v[58:61], v146 offset:1024
	ds_read_b128 v[62:65], v146 offset:2048
	ds_read_b128 v[146:149], v146 offset:3072
	ds_read_b128 v[150:153], v162
	ds_read_b128 v[154:157], v162 offset:1024
	ds_read_b128 v[158:161], v162 offset:2048
	ds_read_b128 v[162:165], v162 offset:3072
	s_add_u32 s42, s62, s42
	s_addc_u32 s43, s63, s31
	v_lshl_add_u64 v[206:207], s[42:43], 0, v[194:195]
	s_add_i32 m0, s24, 0xc000
	ds_read_b128 v[166:169], v45
	ds_read_b128 v[170:173], v45 offset:1024
	ds_read_b128 v[174:177], v45 offset:2048
	ds_read_b128 v[178:181], v45 offset:3072
	ds_read_b128 v[182:185], v45 offset:4096
	ds_read_b128 v[186:189], v45 offset:5120
	ds_read_b128 v[190:193], v45 offset:6144
	ds_read_b128 v[202:205], v45 offset:7168
	global_load_lds_dwordx4 v[206:207], off
	v_lshl_add_u64 v[206:207], s[42:43], 0, v[42:43]
	s_add_i32 m0, s24, 0xe000
	s_nop 0
	global_load_lds_dwordx4 v[206:207], off
	s_waitcnt vmcnt(8)
	s_waitcnt lgkmcnt(0)
	.p2align 3
	s_setprio 1
	s_barrier
	v_mfma_f32_16x16x32_bf16 v[142:145], v[46:49], v[166:169], v[142:145]
	v_mfma_f32_16x16x32_bf16 v[142:145], v[58:61], v[170:173], v[142:145]
	v_mfma_f32_16x16x32_bf16 v[126:129], v[58:61], v[178:181], v[126:129]
	v_mfma_f32_16x16x32_bf16 v[126:129], v[46:49], v[174:177], v[126:129]
	v_mfma_f32_16x16x32_bf16 v[110:113], v[46:49], v[182:185], v[110:113]
	v_mfma_f32_16x16x32_bf16 v[110:113], v[58:61], v[186:189], v[110:113]
	v_mfma_f32_16x16x32_bf16 v[94:97], v[58:61], v[202:205], v[94:97]
	v_mfma_f32_16x16x32_bf16 v[94:97], v[46:49], v[190:193], v[94:97]
	v_mfma_f32_16x16x32_bf16 v[90:93], v[62:65], v[190:193], v[90:93]
	v_mfma_f32_16x16x32_bf16 v[90:93], v[146:149], v[202:205], v[90:93]
	v_mfma_f32_16x16x32_bf16 v[106:109], v[146:149], v[186:189], v[106:109]
	v_mfma_f32_16x16x32_bf16 v[106:109], v[62:65], v[182:185], v[106:109]
	v_mfma_f32_16x16x32_bf16 v[122:125], v[62:65], v[174:177], v[122:125]
	v_mfma_f32_16x16x32_bf16 v[122:125], v[146:149], v[178:181], v[122:125]
	v_mfma_f32_16x16x32_bf16 v[138:141], v[146:149], v[170:173], v[138:141]
	v_mfma_f32_16x16x32_bf16 v[138:141], v[62:65], v[166:169], v[138:141]
	v_mfma_f32_16x16x32_bf16 v[134:137], v[150:153], v[166:169], v[134:137]
	v_mfma_f32_16x16x32_bf16 v[134:137], v[154:157], v[170:173], v[134:137]
	v_mfma_f32_16x16x32_bf16 v[118:121], v[154:157], v[178:181], v[118:121]
	v_mfma_f32_16x16x32_bf16 v[118:121], v[150:153], v[174:177], v[118:121]
	v_mfma_f32_16x16x32_bf16 v[102:105], v[150:153], v[182:185], v[102:105]
	v_mfma_f32_16x16x32_bf16 v[102:105], v[154:157], v[186:189], v[102:105]
	v_mfma_f32_16x16x32_bf16 v[86:89], v[154:157], v[202:205], v[86:89]
	v_mfma_f32_16x16x32_bf16 v[86:89], v[150:153], v[190:193], v[86:89]
	v_mfma_f32_16x16x32_bf16 v[82:85], v[158:161], v[190:193], v[82:85]
	v_mfma_f32_16x16x32_bf16 v[82:85], v[162:165], v[202:205], v[82:85]
	v_mfma_f32_16x16x32_bf16 v[98:101], v[162:165], v[186:189], v[98:101]
	v_mfma_f32_16x16x32_bf16 v[98:101], v[158:161], v[182:185], v[98:101]
	v_mfma_f32_16x16x32_bf16 v[114:117], v[158:161], v[174:177], v[114:117]
	v_mfma_f32_16x16x32_bf16 v[114:117], v[162:165], v[178:181], v[114:117]
	v_mfma_f32_16x16x32_bf16 v[130:133], v[162:165], v[170:173], v[130:133]
	v_mfma_f32_16x16x32_bf16 v[130:133], v[158:161], v[166:169], v[130:133]
	s_barrier
	s_setprio 0
	s_add_i32 s31, s44, s23
	v_lshl_add_u64 v[206:207], s[20:21], 0, v[194:195]
	s_mov_b32 m0, s31
	ds_read_b128 v[166:169], v45 offset:16384
	ds_read_b128 v[170:173], v45 offset:17408
	ds_read_b128 v[174:177], v45 offset:18432
	ds_read_b128 v[178:181], v45 offset:19456
	ds_read_b128 v[182:185], v45 offset:20480
	ds_read_b128 v[186:189], v45 offset:21504
	ds_read_b128 v[190:193], v45 offset:22528
	ds_read_b128 v[202:205], v45 offset:23552
	global_load_lds_dwordx4 v[206:207], off
	s_add_i32 m0, s31, 0x2000
	s_add_u32 s42, s20, 0x4000
	v_lshl_add_u64 v[206:207], s[20:21], 0, v[42:43]
	s_addc_u32 s43, s21, 0
	s_add_i32 s31, s45, s23
	global_load_lds_dwordx4 v[206:207], off
	v_lshl_add_u64 v[206:207], s[42:43], 0, v[194:195]
	s_mov_b32 m0, s31
	s_nop 0
	global_load_lds_dwordx4 v[206:207], off
	v_lshl_add_u64 v[206:207], s[42:43], 0, v[42:43]
	s_add_i32 m0, s31, 0x2000
	s_nop 0
	global_load_lds_dwordx4 v[206:207], off
	v_lshl_add_u64 v[206:207], s[16:17], 0, v[194:195]
	s_mov_b32 m0, s24
	s_nop 0
	global_load_lds_dwordx4 v[206:207], off
	v_lshl_add_u64 v[206:207], s[16:17], 0, v[42:43]
	s_mov_b32 m0, s25
	s_nop 0
	global_load_lds_dwordx4 v[206:207], off
	s_waitcnt vmcnt(8)
	s_waitcnt lgkmcnt(0)
	.p2align 3
	s_setprio 1
	s_barrier
	v_mfma_f32_16x16x32_bf16 v[78:81], v[46:49], v[166:169], v[78:81]
	v_mfma_f32_16x16x32_bf16 v[78:81], v[58:61], v[170:173], v[78:81]
	v_mfma_f32_16x16x32_bf16 v[54:57], v[58:61], v[178:181], v[54:57]
	v_mfma_f32_16x16x32_bf16 v[54:57], v[46:49], v[174:177], v[54:57]
	v_mfma_f32_16x16x32_bf16 v[30:33], v[46:49], v[182:185], v[30:33]
	v_mfma_f32_16x16x32_bf16 v[30:33], v[58:61], v[186:189], v[30:33]
	v_mfma_f32_16x16x32_bf16 v[14:17], v[58:61], v[202:205], v[14:17]
	v_mfma_f32_16x16x32_bf16 v[14:17], v[46:49], v[190:193], v[14:17]
	v_mfma_f32_16x16x32_bf16 v[10:13], v[62:65], v[190:193], v[10:13]
	v_mfma_f32_16x16x32_bf16 v[10:13], v[146:149], v[202:205], v[10:13]
	v_mfma_f32_16x16x32_bf16 v[26:29], v[146:149], v[186:189], v[26:29]
	v_mfma_f32_16x16x32_bf16 v[26:29], v[62:65], v[182:185], v[26:29]
	v_mfma_f32_16x16x32_bf16 v[50:53], v[62:65], v[174:177], v[50:53]
	v_mfma_f32_16x16x32_bf16 v[50:53], v[146:149], v[178:181], v[50:53]
	v_mfma_f32_16x16x32_bf16 v[74:77], v[146:149], v[170:173], v[74:77]
	v_mfma_f32_16x16x32_bf16 v[74:77], v[62:65], v[166:169], v[74:77]
	v_mfma_f32_16x16x32_bf16 v[38:41], v[150:153], v[174:177], v[38:41]
	v_mfma_f32_16x16x32_bf16 v[34:37], v[158:161], v[174:177], v[34:37]
	v_mfma_f32_16x16x32_bf16 v[22:25], v[150:153], v[182:185], v[22:25]
	v_mfma_f32_16x16x32_bf16 v[18:21], v[158:161], v[182:185], v[18:21]
	v_mfma_f32_16x16x32_bf16 v[6:9], v[150:153], v[190:193], v[6:9]
	v_mfma_f32_16x16x32_bf16 v[2:5], v[158:161], v[190:193], v[2:5]
	v_mfma_f32_16x16x32_bf16 v[46:49], v[150:153], v[166:169], v[70:73]
	v_mfma_f32_16x16x32_bf16 v[58:61], v[158:161], v[166:169], v[66:69]
	v_mfma_f32_16x16x32_bf16 v[38:41], v[154:157], v[178:181], v[38:41]
	v_mfma_f32_16x16x32_bf16 v[34:37], v[162:165], v[178:181], v[34:37]
	v_mfma_f32_16x16x32_bf16 v[22:25], v[154:157], v[186:189], v[22:25]
	v_mfma_f32_16x16x32_bf16 v[18:21], v[162:165], v[186:189], v[18:21]
	v_mfma_f32_16x16x32_bf16 v[6:9], v[154:157], v[202:205], v[6:9]
	v_mfma_f32_16x16x32_bf16 v[2:5], v[162:165], v[202:205], v[2:5]
	v_mfma_f32_16x16x32_bf16 v[46:49], v[154:157], v[170:173], v[46:49]
	v_mfma_f32_16x16x32_bf16 v[58:61], v[162:165], v[170:173], v[58:61]
	s_barrier
	s_setprio 0
	s_add_i32 s31, 0, 0x18000
	s_add_i32 s42, 0, 0x1c000
	v_add_u32_e32 v146, s31, v44
	v_add_u32_e32 v162, s42, v44
	ds_read_b128 v[62:65], v146
	ds_read_b128 v[66:69], v146 offset:1024
	ds_read_b128 v[70:73], v146 offset:2048
	ds_read_b128 v[146:149], v146 offset:3072
	ds_read_b128 v[150:153], v162
	ds_read_b128 v[154:157], v162 offset:1024
	ds_read_b128 v[158:161], v162 offset:2048
	ds_read_b128 v[162:165], v162 offset:3072
	s_add_u32 s16, s16, 0x4000
	s_addc_u32 s17, s17, 0
	s_mov_b32 m0, s26
	v_lshl_add_u64 v[206:207], s[16:17], 0, v[194:195]
	ds_read_b128 v[166:169], v45 offset:32768
	ds_read_b128 v[170:173], v45 offset:33792
	ds_read_b128 v[174:177], v45 offset:34816
	ds_read_b128 v[178:181], v45 offset:35840
	ds_read_b128 v[182:185], v45 offset:36864
	ds_read_b128 v[186:189], v45 offset:37888
	ds_read_b128 v[190:193], v45 offset:38912
	ds_read_b128 v[202:205], v45 offset:39936
	global_load_lds_dwordx4 v[206:207], off
	v_lshl_add_u64 v[206:207], s[16:17], 0, v[42:43]
	s_mov_b32 m0, s27
	s_nop 0
	global_load_lds_dwordx4 v[206:207], off
	s_waitcnt vmcnt(8)
	s_waitcnt lgkmcnt(0)
	.p2align 3
	s_setprio 1
	s_barrier
	v_mfma_f32_16x16x32_bf16 v[142:145], v[62:65], v[166:169], v[142:145]
	v_mfma_f32_16x16x32_bf16 v[142:145], v[66:69], v[170:173], v[142:145]
	v_mfma_f32_16x16x32_bf16 v[126:129], v[66:69], v[178:181], v[126:129]
	v_mfma_f32_16x16x32_bf16 v[126:129], v[62:65], v[174:177], v[126:129]
	v_mfma_f32_16x16x32_bf16 v[110:113], v[62:65], v[182:185], v[110:113]
	v_mfma_f32_16x16x32_bf16 v[110:113], v[66:69], v[186:189], v[110:113]
	v_mfma_f32_16x16x32_bf16 v[94:97], v[66:69], v[202:205], v[94:97]
	v_mfma_f32_16x16x32_bf16 v[94:97], v[62:65], v[190:193], v[94:97]
	v_mfma_f32_16x16x32_bf16 v[90:93], v[70:73], v[190:193], v[90:93]
	v_mfma_f32_16x16x32_bf16 v[90:93], v[146:149], v[202:205], v[90:93]
	v_mfma_f32_16x16x32_bf16 v[106:109], v[146:149], v[186:189], v[106:109]
	v_mfma_f32_16x16x32_bf16 v[106:109], v[70:73], v[182:185], v[106:109]
	v_mfma_f32_16x16x32_bf16 v[122:125], v[70:73], v[174:177], v[122:125]
	v_mfma_f32_16x16x32_bf16 v[122:125], v[146:149], v[178:181], v[122:125]
	v_mfma_f32_16x16x32_bf16 v[138:141], v[146:149], v[170:173], v[138:141]
	v_mfma_f32_16x16x32_bf16 v[138:141], v[70:73], v[166:169], v[138:141]
	v_mfma_f32_16x16x32_bf16 v[134:137], v[150:153], v[166:169], v[134:137]
	v_mfma_f32_16x16x32_bf16 v[134:137], v[154:157], v[170:173], v[134:137]
	v_mfma_f32_16x16x32_bf16 v[118:121], v[154:157], v[178:181], v[118:121]
	v_mfma_f32_16x16x32_bf16 v[118:121], v[150:153], v[174:177], v[118:121]
	v_mfma_f32_16x16x32_bf16 v[102:105], v[150:153], v[182:185], v[102:105]
	v_mfma_f32_16x16x32_bf16 v[102:105], v[154:157], v[186:189], v[102:105]
	v_mfma_f32_16x16x32_bf16 v[86:89], v[154:157], v[202:205], v[86:89]
	v_mfma_f32_16x16x32_bf16 v[86:89], v[150:153], v[190:193], v[86:89]
	v_mfma_f32_16x16x32_bf16 v[82:85], v[158:161], v[190:193], v[82:85]
	v_mfma_f32_16x16x32_bf16 v[82:85], v[162:165], v[202:205], v[82:85]
	v_mfma_f32_16x16x32_bf16 v[98:101], v[162:165], v[186:189], v[98:101]
	v_mfma_f32_16x16x32_bf16 v[98:101], v[158:161], v[182:185], v[98:101]
	v_mfma_f32_16x16x32_bf16 v[114:117], v[158:161], v[174:177], v[114:117]
	v_mfma_f32_16x16x32_bf16 v[114:117], v[162:165], v[178:181], v[114:117]
	v_mfma_f32_16x16x32_bf16 v[130:133], v[162:165], v[170:173], v[130:133]
	v_mfma_f32_16x16x32_bf16 v[130:133], v[158:161], v[166:169], v[130:133]
	s_barrier
	s_setprio 0
	s_add_u32 s16, s20, 0x40000
	s_addc_u32 s17, s21, 0
	s_add_i32 s31, s31, s23
	v_lshl_add_u64 v[206:207], s[16:17], 0, v[194:195]
	s_mov_b32 m0, s31
	ds_read_b128 v[166:169], v45 offset:49152
	ds_read_b128 v[170:173], v45 offset:50176
	ds_read_b128 v[174:177], v45 offset:51200
	ds_read_b128 v[178:181], v45 offset:52224
	ds_read_b128 v[182:185], v45 offset:53248
	ds_read_b128 v[186:189], v45 offset:54272
	ds_read_b128 v[190:193], v45 offset:55296
	ds_read_b128 v[202:205], v45 offset:56320
	global_load_lds_dwordx4 v[206:207], off
	s_add_i32 m0, s31, 0x2000
	v_lshl_add_u64 v[206:207], s[16:17], 0, v[42:43]
	s_add_u32 s16, s20, 0x44000
	s_addc_u32 s17, s21, 0
	s_add_i32 s20, s42, s23
	global_load_lds_dwordx4 v[206:207], off
	v_lshl_add_u64 v[206:207], s[16:17], 0, v[194:195]
	s_mov_b32 m0, s20
	s_nop 0
	global_load_lds_dwordx4 v[206:207], off
	v_lshl_add_u64 v[206:207], s[16:17], 0, v[42:43]
	s_add_i32 m0, s20, 0x2000
	s_nop 0
	global_load_lds_dwordx4 v[206:207], off
	v_lshl_add_u64 v[206:207], s[18:19], 0, v[194:195]
	s_mov_b32 m0, s28
	s_nop 0
	global_load_lds_dwordx4 v[206:207], off
	v_lshl_add_u64 v[206:207], s[18:19], 0, v[42:43]
	s_mov_b32 m0, s29
	s_nop 0
	global_load_lds_dwordx4 v[206:207], off
	s_waitcnt vmcnt(8)
	s_waitcnt lgkmcnt(0)
	.p2align 3
	s_setprio 1
	s_barrier
	v_mfma_f32_16x16x32_bf16 v[78:81], v[62:65], v[166:169], v[78:81]
	v_mfma_f32_16x16x32_bf16 v[78:81], v[66:69], v[170:173], v[78:81]
	v_mfma_f32_16x16x32_bf16 v[54:57], v[66:69], v[178:181], v[54:57]
	v_mfma_f32_16x16x32_bf16 v[54:57], v[62:65], v[174:177], v[54:57]
	v_mfma_f32_16x16x32_bf16 v[30:33], v[62:65], v[182:185], v[30:33]
	v_mfma_f32_16x16x32_bf16 v[30:33], v[66:69], v[186:189], v[30:33]
	v_mfma_f32_16x16x32_bf16 v[14:17], v[66:69], v[202:205], v[14:17]
	v_mfma_f32_16x16x32_bf16 v[14:17], v[62:65], v[190:193], v[14:17]
	v_mfma_f32_16x16x32_bf16 v[10:13], v[70:73], v[190:193], v[10:13]
	v_mfma_f32_16x16x32_bf16 v[10:13], v[146:149], v[202:205], v[10:13]
	v_mfma_f32_16x16x32_bf16 v[26:29], v[146:149], v[186:189], v[26:29]
	v_mfma_f32_16x16x32_bf16 v[26:29], v[70:73], v[182:185], v[26:29]
	v_mfma_f32_16x16x32_bf16 v[50:53], v[70:73], v[174:177], v[50:53]
	v_mfma_f32_16x16x32_bf16 v[50:53], v[146:149], v[178:181], v[50:53]
	v_mfma_f32_16x16x32_bf16 v[74:77], v[146:149], v[170:173], v[74:77]
	v_mfma_f32_16x16x32_bf16 v[74:77], v[70:73], v[166:169], v[74:77]
	v_mfma_f32_16x16x32_bf16 v[46:49], v[150:153], v[166:169], v[46:49]
	v_mfma_f32_16x16x32_bf16 v[70:73], v[154:157], v[170:173], v[46:49]
	v_mfma_f32_16x16x32_bf16 v[46:49], v[158:161], v[166:169], v[58:61]
	v_mfma_f32_16x16x32_bf16 v[38:41], v[150:153], v[174:177], v[38:41]
	v_mfma_f32_16x16x32_bf16 v[34:37], v[158:161], v[174:177], v[34:37]
	v_mfma_f32_16x16x32_bf16 v[22:25], v[150:153], v[182:185], v[22:25]
	v_mfma_f32_16x16x32_bf16 v[18:21], v[158:161], v[182:185], v[18:21]
	v_mfma_f32_16x16x32_bf16 v[6:9], v[150:153], v[190:193], v[6:9]
	v_mfma_f32_16x16x32_bf16 v[2:5], v[158:161], v[190:193], v[2:5]
	v_mfma_f32_16x16x32_bf16 v[66:69], v[162:165], v[170:173], v[46:49]
	v_mfma_f32_16x16x32_bf16 v[38:41], v[154:157], v[178:181], v[38:41]
	v_mfma_f32_16x16x32_bf16 v[34:37], v[162:165], v[178:181], v[34:37]
	v_mfma_f32_16x16x32_bf16 v[22:25], v[154:157], v[186:189], v[22:25]
	v_mfma_f32_16x16x32_bf16 v[18:21], v[162:165], v[186:189], v[18:21]
	v_mfma_f32_16x16x32_bf16 v[6:9], v[154:157], v[202:205], v[6:9]
	v_mfma_f32_16x16x32_bf16 v[2:5], v[162:165], v[202:205], v[2:5]
	s_barrier
	s_setprio 0
	s_cmp_gt_u32 s30, 61
	s_mov_b32 s30, s4
	s_cbranch_scc1 .LBB0_1349

.LBB0_1502:
	s_or_b32 s82, s81, 1
	s_add_u32 vcc_lo, s26, vcc_lo
	s_addc_u32 vcc_hi, s27, vcc_hi
	s_and_b64 s[46:47], exec, s[46:47]
	s_cselect_b32 vcc_hi, s19, vcc_hi
	s_cselect_b32 vcc_lo, s21, vcc_lo
	s_add_u32 s46, s44, 0x280000
	s_addc_u32 s47, s45, 0
	s_add_i32 s88, 0, 0x10000
	s_add_i32 s89, 0, 0x14000
	v_add_u32_e32 v62, s88, v184
	v_add_u32_e32 v160, s89, v184
	ds_read_b128 v[50:53], v62
	ds_read_b128 v[54:57], v62 offset:1024
	ds_read_b128 v[58:61], v62 offset:2048
	ds_read_b128 v[62:65], v62 offset:3072
	ds_read_b128 v[146:149], v160
	ds_read_b128 v[150:153], v160 offset:1024
	ds_read_b128 v[156:159], v160 offset:2048
	ds_read_b128 v[160:163], v160 offset:3072
	s_mul_hi_u32 s83, s82, 0x280000
	s_mul_i32 s82, s82, 0x280000
	s_add_u32 s82, s79, s82
	s_addc_u32 s83, s80, s83
	v_lshl_add_u64 v[206:207], s[82:83], 0, v[194:195]
	s_add_i32 m0, s68, 0xc000
	ds_read_b128 v[164:167], v185
	ds_read_b128 v[168:171], v185 offset:1024
	ds_read_b128 v[172:175], v185 offset:2048
	ds_read_b128 v[176:179], v185 offset:3072
	ds_read_b128 v[180:183], v185 offset:4096
	ds_read_b128 v[186:189], v185 offset:5120
	ds_read_b128 v[190:193], v185 offset:6144
	ds_read_b128 v[202:205], v185 offset:7168
	global_load_lds_dwordx4 v[206:207], off
	v_lshl_add_u64 v[206:207], s[82:83], 0, v[154:155]
	s_add_i32 m0, s68, 0xe000
	s_nop 0
	global_load_lds_dwordx4 v[206:207], off
	s_waitcnt vmcnt(8)
	s_waitcnt lgkmcnt(0)
	.p2align 3
	s_setprio 1
	s_barrier
	v_mfma_f32_16x16x32_bf16 v[142:145], v[50:53], v[164:167], v[142:145]
	v_mfma_f32_16x16x32_bf16 v[142:145], v[54:57], v[168:171], v[142:145]
	v_mfma_f32_16x16x32_bf16 v[126:129], v[54:57], v[176:179], v[126:129]
	v_mfma_f32_16x16x32_bf16 v[126:129], v[50:53], v[172:175], v[126:129]
	v_mfma_f32_16x16x32_bf16 v[110:113], v[50:53], v[180:183], v[110:113]
	v_mfma_f32_16x16x32_bf16 v[110:113], v[54:57], v[186:189], v[110:113]
	v_mfma_f32_16x16x32_bf16 v[94:97], v[54:57], v[202:205], v[94:97]
	v_mfma_f32_16x16x32_bf16 v[94:97], v[50:53], v[190:193], v[94:97]
	v_mfma_f32_16x16x32_bf16 v[90:93], v[58:61], v[190:193], v[90:93]
	v_mfma_f32_16x16x32_bf16 v[90:93], v[62:65], v[202:205], v[90:93]
	v_mfma_f32_16x16x32_bf16 v[106:109], v[62:65], v[186:189], v[106:109]
	v_mfma_f32_16x16x32_bf16 v[106:109], v[58:61], v[180:183], v[106:109]
	v_mfma_f32_16x16x32_bf16 v[122:125], v[58:61], v[172:175], v[122:125]
	v_mfma_f32_16x16x32_bf16 v[122:125], v[62:65], v[176:179], v[122:125]
	v_mfma_f32_16x16x32_bf16 v[138:141], v[62:65], v[168:171], v[138:141]
	v_mfma_f32_16x16x32_bf16 v[138:141], v[58:61], v[164:167], v[138:141]
	v_mfma_f32_16x16x32_bf16 v[134:137], v[146:149], v[164:167], v[134:137]
	v_mfma_f32_16x16x32_bf16 v[134:137], v[150:153], v[168:171], v[134:137]
	v_mfma_f32_16x16x32_bf16 v[118:121], v[150:153], v[176:179], v[118:121]
	v_mfma_f32_16x16x32_bf16 v[118:121], v[146:149], v[172:175], v[118:121]
	v_mfma_f32_16x16x32_bf16 v[102:105], v[146:149], v[180:183], v[102:105]
	v_mfma_f32_16x16x32_bf16 v[102:105], v[150:153], v[186:189], v[102:105]
	v_mfma_f32_16x16x32_bf16 v[86:89], v[150:153], v[202:205], v[86:89]
	v_mfma_f32_16x16x32_bf16 v[86:89], v[146:149], v[190:193], v[86:89]
	v_mfma_f32_16x16x32_bf16 v[82:85], v[156:159], v[190:193], v[82:85]
	v_mfma_f32_16x16x32_bf16 v[82:85], v[160:163], v[202:205], v[82:85]
	v_mfma_f32_16x16x32_bf16 v[98:101], v[160:163], v[186:189], v[98:101]
	v_mfma_f32_16x16x32_bf16 v[98:101], v[156:159], v[180:183], v[98:101]
	v_mfma_f32_16x16x32_bf16 v[114:117], v[156:159], v[172:175], v[114:117]
	v_mfma_f32_16x16x32_bf16 v[114:117], v[160:163], v[176:179], v[114:117]
	v_mfma_f32_16x16x32_bf16 v[130:133], v[160:163], v[168:171], v[130:133]
	v_mfma_f32_16x16x32_bf16 v[130:133], v[156:159], v[164:167], v[130:133]
	s_barrier
	s_setprio 0
	s_add_i32 s82, s88, s67
	v_lshl_add_u64 v[206:207], vcc, 0, v[194:195]
	s_mov_b32 m0, s82
	ds_read_b128 v[164:167], v185 offset:16384
	ds_read_b128 v[168:171], v185 offset:17408
	ds_read_b128 v[172:175], v185 offset:18432
	ds_read_b128 v[176:179], v185 offset:19456
	ds_read_b128 v[180:183], v185 offset:20480
	ds_read_b128 v[186:189], v185 offset:21504
	ds_read_b128 v[190:193], v185 offset:22528
	ds_read_b128 v[202:205], v185 offset:23552
	global_load_lds_dwordx4 v[206:207], off
	s_add_i32 m0, s82, 0x2000
	s_add_u32 s82, vcc_lo, 0x4000
	v_lshl_add_u64 v[206:207], vcc, 0, v[154:155]
	s_addc_u32 s83, vcc_hi, 0
	s_add_i32 s88, s89, s67
	global_load_lds_dwordx4 v[206:207], off
	v_lshl_add_u64 v[206:207], s[82:83], 0, v[194:195]
	s_mov_b32 m0, s88
	s_nop 0
	global_load_lds_dwordx4 v[206:207], off
	v_lshl_add_u64 v[206:207], s[82:83], 0, v[154:155]
	s_add_i32 m0, s88, 0x2000
	s_nop 0
	global_load_lds_dwordx4 v[206:207], off
	v_lshl_add_u64 v[206:207], s[44:45], 0, v[194:195]
	s_mov_b32 m0, s68
	s_nop 0
	global_load_lds_dwordx4 v[206:207], off
	v_lshl_add_u64 v[206:207], s[44:45], 0, v[154:155]
	s_mov_b32 m0, s69
	s_nop 0
	global_load_lds_dwordx4 v[206:207], off
	s_waitcnt vmcnt(8)
	s_waitcnt lgkmcnt(0)
	.p2align 3
	s_setprio 1
	s_barrier
	v_mfma_f32_16x16x32_bf16 v[78:81], v[50:53], v[164:167], v[78:81]
	v_mfma_f32_16x16x32_bf16 v[78:81], v[54:57], v[168:171], v[78:81]
	v_mfma_f32_16x16x32_bf16 v[46:49], v[54:57], v[176:179], v[46:49]
	v_mfma_f32_16x16x32_bf16 v[46:49], v[50:53], v[172:175], v[46:49]
	v_mfma_f32_16x16x32_bf16 v[30:33], v[50:53], v[180:183], v[30:33]
	v_mfma_f32_16x16x32_bf16 v[30:33], v[54:57], v[186:189], v[30:33]
	v_mfma_f32_16x16x32_bf16 v[14:17], v[54:57], v[202:205], v[14:17]
	v_mfma_f32_16x16x32_bf16 v[14:17], v[50:53], v[190:193], v[14:17]
	v_mfma_f32_16x16x32_bf16 v[10:13], v[58:61], v[190:193], v[10:13]
	v_mfma_f32_16x16x32_bf16 v[10:13], v[62:65], v[202:205], v[10:13]
	v_mfma_f32_16x16x32_bf16 v[26:29], v[62:65], v[186:189], v[26:29]
	v_mfma_f32_16x16x32_bf16 v[26:29], v[58:61], v[180:183], v[26:29]
	v_mfma_f32_16x16x32_bf16 v[42:45], v[58:61], v[172:175], v[42:45]
	v_mfma_f32_16x16x32_bf16 v[42:45], v[62:65], v[176:179], v[42:45]
	v_mfma_f32_16x16x32_bf16 v[74:77], v[62:65], v[168:171], v[74:77]
	v_mfma_f32_16x16x32_bf16 v[74:77], v[58:61], v[164:167], v[74:77]
	v_mfma_f32_16x16x32_bf16 v[38:41], v[146:149], v[172:175], v[38:41]
	v_mfma_f32_16x16x32_bf16 v[34:37], v[156:159], v[172:175], v[34:37]
	v_mfma_f32_16x16x32_bf16 v[22:25], v[146:149], v[180:183], v[22:25]
	v_mfma_f32_16x16x32_bf16 v[18:21], v[156:159], v[180:183], v[18:21]
	v_mfma_f32_16x16x32_bf16 v[6:9], v[146:149], v[190:193], v[6:9]
	v_mfma_f32_16x16x32_bf16 v[2:5], v[156:159], v[190:193], v[2:5]
	v_mfma_f32_16x16x32_bf16 v[50:53], v[146:149], v[164:167], v[70:73]
	v_mfma_f32_16x16x32_bf16 v[54:57], v[156:159], v[164:167], v[66:69]
	v_mfma_f32_16x16x32_bf16 v[38:41], v[150:153], v[176:179], v[38:41]
	v_mfma_f32_16x16x32_bf16 v[34:37], v[160:163], v[176:179], v[34:37]
	v_mfma_f32_16x16x32_bf16 v[22:25], v[150:153], v[186:189], v[22:25]
	v_mfma_f32_16x16x32_bf16 v[18:21], v[160:163], v[186:189], v[18:21]
	v_mfma_f32_16x16x32_bf16 v[6:9], v[150:153], v[202:205], v[6:9]
	v_mfma_f32_16x16x32_bf16 v[2:5], v[160:163], v[202:205], v[2:5]
	v_mfma_f32_16x16x32_bf16 v[50:53], v[150:153], v[168:171], v[50:53]
	v_mfma_f32_16x16x32_bf16 v[54:57], v[160:163], v[168:171], v[54:57]
	s_barrier
	s_setprio 0
	s_add_i32 s82, 0, 0x18000
	s_add_i32 s83, 0, 0x1c000
	v_add_u32_e32 v70, s82, v184
	v_add_u32_e32 v160, s83, v184
	ds_read_b128 v[58:61], v70
	ds_read_b128 v[62:65], v70 offset:1024
	ds_read_b128 v[66:69], v70 offset:2048
	ds_read_b128 v[70:73], v70 offset:3072
	ds_read_b128 v[146:149], v160
	ds_read_b128 v[150:153], v160 offset:1024
	ds_read_b128 v[156:159], v160 offset:2048
	ds_read_b128 v[160:163], v160 offset:3072
	s_add_u32 s44, s44, 0x4000
	s_addc_u32 s45, s45, 0
	s_mov_b32 m0, s72
	v_lshl_add_u64 v[206:207], s[44:45], 0, v[194:195]
	ds_read_b128 v[164:167], v185 offset:32768
	ds_read_b128 v[168:171], v185 offset:33792
	ds_read_b128 v[172:175], v185 offset:34816
	ds_read_b128 v[176:179], v185 offset:35840
	ds_read_b128 v[180:183], v185 offset:36864
	ds_read_b128 v[186:189], v185 offset:37888
	ds_read_b128 v[190:193], v185 offset:38912
	ds_read_b128 v[202:205], v185 offset:39936
	global_load_lds_dwordx4 v[206:207], off
	v_lshl_add_u64 v[206:207], s[44:45], 0, v[154:155]
	s_mov_b32 m0, s73
	s_nop 0
	global_load_lds_dwordx4 v[206:207], off
	s_waitcnt vmcnt(8)
	s_waitcnt lgkmcnt(0)
	.p2align 3
	s_setprio 1
	s_barrier
	v_mfma_f32_16x16x32_bf16 v[142:145], v[58:61], v[164:167], v[142:145]
	v_mfma_f32_16x16x32_bf16 v[142:145], v[62:65], v[168:171], v[142:145]
	v_mfma_f32_16x16x32_bf16 v[126:129], v[62:65], v[176:179], v[126:129]
	v_mfma_f32_16x16x32_bf16 v[126:129], v[58:61], v[172:175], v[126:129]
	v_mfma_f32_16x16x32_bf16 v[110:113], v[58:61], v[180:183], v[110:113]
	v_mfma_f32_16x16x32_bf16 v[110:113], v[62:65], v[186:189], v[110:113]
	v_mfma_f32_16x16x32_bf16 v[94:97], v[62:65], v[202:205], v[94:97]
	v_mfma_f32_16x16x32_bf16 v[94:97], v[58:61], v[190:193], v[94:97]
	v_mfma_f32_16x16x32_bf16 v[90:93], v[66:69], v[190:193], v[90:93]
	v_mfma_f32_16x16x32_bf16 v[90:93], v[70:73], v[202:205], v[90:93]
	v_mfma_f32_16x16x32_bf16 v[106:109], v[70:73], v[186:189], v[106:109]
	v_mfma_f32_16x16x32_bf16 v[106:109], v[66:69], v[180:183], v[106:109]
	v_mfma_f32_16x16x32_bf16 v[122:125], v[66:69], v[172:175], v[122:125]
	v_mfma_f32_16x16x32_bf16 v[122:125], v[70:73], v[176:179], v[122:125]
	v_mfma_f32_16x16x32_bf16 v[138:141], v[70:73], v[168:171], v[138:141]
	v_mfma_f32_16x16x32_bf16 v[138:141], v[66:69], v[164:167], v[138:141]
	v_mfma_f32_16x16x32_bf16 v[134:137], v[146:149], v[164:167], v[134:137]
	v_mfma_f32_16x16x32_bf16 v[134:137], v[150:153], v[168:171], v[134:137]
	v_mfma_f32_16x16x32_bf16 v[118:121], v[150:153], v[176:179], v[118:121]
	v_mfma_f32_16x16x32_bf16 v[118:121], v[146:149], v[172:175], v[118:121]
	v_mfma_f32_16x16x32_bf16 v[102:105], v[146:149], v[180:183], v[102:105]
	v_mfma_f32_16x16x32_bf16 v[102:105], v[150:153], v[186:189], v[102:105]
	v_mfma_f32_16x16x32_bf16 v[86:89], v[150:153], v[202:205], v[86:89]
	v_mfma_f32_16x16x32_bf16 v[86:89], v[146:149], v[190:193], v[86:89]
	v_mfma_f32_16x16x32_bf16 v[82:85], v[156:159], v[190:193], v[82:85]
	v_mfma_f32_16x16x32_bf16 v[82:85], v[160:163], v[202:205], v[82:85]
	v_mfma_f32_16x16x32_bf16 v[98:101], v[160:163], v[186:189], v[98:101]
	v_mfma_f32_16x16x32_bf16 v[98:101], v[156:159], v[180:183], v[98:101]
	v_mfma_f32_16x16x32_bf16 v[114:117], v[156:159], v[172:175], v[114:117]
	v_mfma_f32_16x16x32_bf16 v[114:117], v[160:163], v[176:179], v[114:117]
	v_mfma_f32_16x16x32_bf16 v[130:133], v[160:163], v[168:171], v[130:133]
	v_mfma_f32_16x16x32_bf16 v[130:133], v[156:159], v[164:167], v[130:133]
	s_barrier
	s_setprio 0
	s_add_u32 s44, vcc_lo, 0x40000
	s_addc_u32 s45, vcc_hi, 0
	s_add_i32 s82, s82, s67
	v_lshl_add_u64 v[206:207], s[44:45], 0, v[194:195]
	s_mov_b32 m0, s82
	ds_read_b128 v[164:167], v185 offset:49152
	ds_read_b128 v[168:171], v185 offset:50176
	ds_read_b128 v[172:175], v185 offset:51200
	ds_read_b128 v[176:179], v185 offset:52224
	ds_read_b128 v[180:183], v185 offset:53248
	ds_read_b128 v[186:189], v185 offset:54272
	ds_read_b128 v[190:193], v185 offset:55296
	ds_read_b128 v[202:205], v185 offset:56320
	global_load_lds_dwordx4 v[206:207], off
	s_add_i32 m0, s82, 0x2000
	v_lshl_add_u64 v[206:207], s[44:45], 0, v[154:155]
	s_add_u32 s44, vcc_lo, 0x44000
	s_addc_u32 s45, vcc_hi, 0
	s_add_i32 s82, s83, s67
	global_load_lds_dwordx4 v[206:207], off
	v_lshl_add_u64 v[206:207], s[44:45], 0, v[194:195]
	s_mov_b32 m0, s82
	s_nop 0
	global_load_lds_dwordx4 v[206:207], off
	v_lshl_add_u64 v[206:207], s[44:45], 0, v[154:155]
	s_add_i32 m0, s82, 0x2000
	s_nop 0
	global_load_lds_dwordx4 v[206:207], off
	v_lshl_add_u64 v[206:207], s[46:47], 0, v[194:195]
	s_mov_b32 m0, s76
	s_nop 0
	global_load_lds_dwordx4 v[206:207], off
	v_lshl_add_u64 v[206:207], s[46:47], 0, v[154:155]
	s_mov_b32 m0, s77
	s_nop 0
	global_load_lds_dwordx4 v[206:207], off
	s_waitcnt vmcnt(8)
	s_waitcnt lgkmcnt(0)
	.p2align 3
	s_setprio 1
	s_barrier
	v_mfma_f32_16x16x32_bf16 v[78:81], v[58:61], v[164:167], v[78:81]
	v_mfma_f32_16x16x32_bf16 v[78:81], v[62:65], v[168:171], v[78:81]
	v_mfma_f32_16x16x32_bf16 v[46:49], v[62:65], v[176:179], v[46:49]
	v_mfma_f32_16x16x32_bf16 v[46:49], v[58:61], v[172:175], v[46:49]
	v_mfma_f32_16x16x32_bf16 v[30:33], v[58:61], v[180:183], v[30:33]
	v_mfma_f32_16x16x32_bf16 v[30:33], v[62:65], v[186:189], v[30:33]
	v_mfma_f32_16x16x32_bf16 v[14:17], v[62:65], v[202:205], v[14:17]
	v_mfma_f32_16x16x32_bf16 v[14:17], v[58:61], v[190:193], v[14:17]
	v_mfma_f32_16x16x32_bf16 v[10:13], v[66:69], v[190:193], v[10:13]
	v_mfma_f32_16x16x32_bf16 v[10:13], v[70:73], v[202:205], v[10:13]
	v_mfma_f32_16x16x32_bf16 v[26:29], v[70:73], v[186:189], v[26:29]
	v_mfma_f32_16x16x32_bf16 v[26:29], v[66:69], v[180:183], v[26:29]
	v_mfma_f32_16x16x32_bf16 v[42:45], v[66:69], v[172:175], v[42:45]
	v_mfma_f32_16x16x32_bf16 v[42:45], v[70:73], v[176:179], v[42:45]
	v_mfma_f32_16x16x32_bf16 v[74:77], v[70:73], v[168:171], v[74:77]
	v_mfma_f32_16x16x32_bf16 v[74:77], v[66:69], v[164:167], v[74:77]
	v_mfma_f32_16x16x32_bf16 v[50:53], v[146:149], v[164:167], v[50:53]
	v_mfma_f32_16x16x32_bf16 v[70:73], v[150:153], v[168:171], v[50:53]
	v_mfma_f32_16x16x32_bf16 v[50:53], v[156:159], v[164:167], v[54:57]
	v_mfma_f32_16x16x32_bf16 v[38:41], v[146:149], v[172:175], v[38:41]
	v_mfma_f32_16x16x32_bf16 v[34:37], v[156:159], v[172:175], v[34:37]
	v_mfma_f32_16x16x32_bf16 v[22:25], v[146:149], v[180:183], v[22:25]
	v_mfma_f32_16x16x32_bf16 v[18:21], v[156:159], v[180:183], v[18:21]
	v_mfma_f32_16x16x32_bf16 v[6:9], v[146:149], v[190:193], v[6:9]
	v_mfma_f32_16x16x32_bf16 v[2:5], v[156:159], v[190:193], v[2:5]
	v_mfma_f32_16x16x32_bf16 v[66:69], v[160:163], v[168:171], v[50:53]
	v_mfma_f32_16x16x32_bf16 v[38:41], v[150:153], v[176:179], v[38:41]
	v_mfma_f32_16x16x32_bf16 v[34:37], v[160:163], v[176:179], v[34:37]
	v_mfma_f32_16x16x32_bf16 v[22:25], v[150:153], v[186:189], v[22:25]
	v_mfma_f32_16x16x32_bf16 v[18:21], v[160:163], v[186:189], v[18:21]
	v_mfma_f32_16x16x32_bf16 v[6:9], v[150:153], v[202:205], v[6:9]
	v_mfma_f32_16x16x32_bf16 v[2:5], v[160:163], v[202:205], v[2:5]
	s_barrier
	s_setprio 0
	s_cmpk_gt_u32 s81, 0x7d
	s_mov_b32 s81, s4
	s_cbranch_scc1 .LBB0_1505
